# K-loop: setprio flips and duplicate post-barrier lgkmcnt wait removed
# speedup vs baseline: 1.0799x; 1.0001x over previous
.LBB0_304:
	s_waitcnt lgkmcnt(0)
	ds_read_b128 v[2:5], v234
	ds_read_b128 v[6:9], v234 offset:1024
	ds_read_b128 v[10:13], v234 offset:2048
	ds_read_b128 v[14:17], v234 offset:3072
	ds_read_b128 v[18:21], v235
	ds_read_b128 v[22:25], v235 offset:1024
	ds_read_b128 v[26:29], v235 offset:2048
	ds_read_b128 v[30:33], v235 offset:3072
	s_add_u32 s6, s4, 0xfff80080
	s_addc_u32 s7, s5, -1
	s_cmp_eq_u32 s80, 28
	s_cselect_b32 s9, s35, s7
	s_cselect_b32 s8, s52, s6
	s_cselect_b32 s7, s31, s79
	s_cselect_b32 s6, s77, s78
	v_lshl_add_u64 v[214:215], s[4:5], 0, v[206:207]
	s_add_i32 m0, s43, 0xc000
	ds_read_b128 v[98:101], v236
	ds_read_b128 v[102:105], v236 offset:1024
	ds_read_b128 v[106:109], v236 offset:2048
	ds_read_b128 v[110:113], v236 offset:3072
	ds_read_b128 v[178:181], v236 offset:4096
	ds_read_b128 v[182:185], v236 offset:5120
	ds_read_b128 v[186:189], v236 offset:6144
	ds_read_b128 v[190:193], v236 offset:7168
	global_load_lds_dwordx4 v[214:215], off
	v_lshl_add_u64 v[214:215], s[4:5], 0, v[208:209]
	s_add_i32 m0, s43, 0xe000
	s_nop 0
	global_load_lds_dwordx4 v[214:215], off
	s_waitcnt vmcnt(8)
	s_waitcnt lgkmcnt(0)
	s_barrier
	v_mfma_i32_16x16x64_i8 v[174:177], v[2:5], v[98:101], v[174:177]
	v_mfma_i32_16x16x64_i8 v[170:173], v[10:13], v[98:101], v[170:173]
	v_mfma_i32_16x16x64_i8 v[158:161], v[2:5], v[106:109], v[158:161]
	v_mfma_i32_16x16x64_i8 v[154:157], v[10:13], v[106:109], v[154:157]
	v_mfma_i32_16x16x64_i8 v[142:145], v[2:5], v[178:181], v[142:145]
	v_mfma_i32_16x16x64_i8 v[138:141], v[10:13], v[178:181], v[138:141]
	v_mfma_i32_16x16x64_i8 v[126:129], v[2:5], v[186:189], v[126:129]
	v_mfma_i32_16x16x64_i8 v[122:125], v[10:13], v[186:189], v[122:125]
	v_mfma_i32_16x16x64_i8 v[174:177], v[6:9], v[102:105], v[174:177]
	v_mfma_i32_16x16x64_i8 v[170:173], v[14:17], v[102:105], v[170:173]
	v_mfma_i32_16x16x64_i8 v[158:161], v[6:9], v[110:113], v[158:161]
	v_mfma_i32_16x16x64_i8 v[154:157], v[14:17], v[110:113], v[154:157]
	v_mfma_i32_16x16x64_i8 v[142:145], v[6:9], v[182:185], v[142:145]
	v_mfma_i32_16x16x64_i8 v[138:141], v[14:17], v[182:185], v[138:141]
	v_mfma_i32_16x16x64_i8 v[126:129], v[6:9], v[190:193], v[126:129]
	v_mfma_i32_16x16x64_i8 v[122:125], v[14:17], v[190:193], v[122:125]
	v_mfma_i32_16x16x64_i8 v[166:169], v[18:21], v[98:101], v[166:169]
	v_mfma_i32_16x16x64_i8 v[98:101], v[26:29], v[98:101], v[162:165]
	v_mfma_i32_16x16x64_i8 v[166:169], v[22:25], v[102:105], v[166:169]
	v_mfma_i32_16x16x64_i8 v[98:101], v[30:33], v[102:105], v[98:101]
	v_mfma_i32_16x16x64_i8 v[102:105], v[18:21], v[106:109], v[150:153]
	v_mfma_i32_16x16x64_i8 v[106:109], v[26:29], v[106:109], v[146:149]
	v_mfma_i32_16x16x64_i8 v[130:133], v[26:29], v[178:181], v[130:133]
	v_mfma_i32_16x16x64_i8 v[118:121], v[18:21], v[186:189], v[118:121]
	v_mfma_i32_16x16x64_i8 v[114:117], v[26:29], v[186:189], v[114:117]
	v_mfma_i32_16x16x64_i8 v[102:105], v[22:25], v[110:113], v[102:105]
	v_mfma_i32_16x16x64_i8 v[106:109], v[30:33], v[110:113], v[106:109]
	v_mfma_i32_16x16x64_i8 v[110:113], v[18:21], v[178:181], v[134:137]
	v_mfma_i32_16x16x64_i8 v[130:133], v[30:33], v[182:185], v[130:133]
	v_mfma_i32_16x16x64_i8 v[118:121], v[22:25], v[190:193], v[118:121]
	v_mfma_i32_16x16x64_i8 v[114:117], v[30:33], v[190:193], v[114:117]
	v_mfma_i32_16x16x64_i8 v[110:113], v[22:25], v[182:185], v[110:113]
	s_barrier
	s_add_i32 s81, s70, s41
	v_lshl_add_u64 v[226:227], s[6:7], 0, v[196:197]
	s_mov_b32 m0, s81
	ds_read_b128 v[134:137], v236 offset:16384
	ds_read_b128 v[146:149], v236 offset:17408
	ds_read_b128 v[150:153], v236 offset:18432
	ds_read_b128 v[162:165], v236 offset:19456
	ds_read_b128 v[178:181], v236 offset:20480
	ds_read_b128 v[182:185], v236 offset:21504
	ds_read_b128 v[186:189], v236 offset:22528
	ds_read_b128 v[190:193], v236 offset:23552
	global_load_lds_dwordx4 v[226:227], off
	s_add_i32 m0, s81, 0x2000
	s_add_u32 s82, s6, 0x80000
	v_lshl_add_u64 v[244:245], s[6:7], 0, v[198:199]
	s_addc_u32 s83, s7, 0
	s_add_i32 s81, s71, s41
	global_load_lds_dwordx4 v[244:245], off
	v_lshl_add_u64 v[214:215], s[82:83], 0, v[196:197]
	s_mov_b32 m0, s81
	v_lshl_add_u64 v[246:247], s[8:9], 0, v[196:197]
	global_load_lds_dwordx4 v[214:215], off
	v_lshl_add_u64 v[214:215], s[82:83], 0, v[198:199]
	s_add_i32 m0, s81, 0x2000
	v_lshl_add_u64 v[248:249], s[8:9], 0, v[198:199]
	global_load_lds_dwordx4 v[214:215], off
	s_mov_b32 m0, s43
	s_nop 0
	global_load_lds_dwordx4 v[246:247], off
	s_mov_b32 m0, s57
	s_nop 0
	global_load_lds_dwordx4 v[248:249], off
	s_waitcnt vmcnt(8)
	s_waitcnt lgkmcnt(0)
	s_barrier
	v_mfma_i32_16x16x64_i8 v[94:97], v[2:5], v[134:137], v[94:97]
	v_mfma_i32_16x16x64_i8 v[90:93], v[10:13], v[134:137], v[90:93]
	v_mfma_i32_16x16x64_i8 v[78:81], v[2:5], v[150:153], v[78:81]
	v_mfma_i32_16x16x64_i8 v[74:77], v[10:13], v[150:153], v[74:77]
	v_mfma_i32_16x16x64_i8 v[62:65], v[2:5], v[178:181], v[62:65]
	v_mfma_i32_16x16x64_i8 v[58:61], v[10:13], v[178:181], v[58:61]
	v_mfma_i32_16x16x64_i8 v[2:5], v[2:5], v[186:189], v[46:49]
	v_mfma_i32_16x16x64_i8 v[94:97], v[6:9], v[146:149], v[94:97]
	v_mfma_i32_16x16x64_i8 v[90:93], v[14:17], v[146:149], v[90:93]
	v_mfma_i32_16x16x64_i8 v[78:81], v[6:9], v[162:165], v[78:81]
	v_mfma_i32_16x16x64_i8 v[74:77], v[14:17], v[162:165], v[74:77]
	v_mfma_i32_16x16x64_i8 v[62:65], v[6:9], v[182:185], v[62:65]
	v_mfma_i32_16x16x64_i8 v[58:61], v[14:17], v[182:185], v[58:61]
	v_mfma_i32_16x16x64_i8 v[2:5], v[6:9], v[190:193], v[2:5]
	v_mfma_i32_16x16x64_i8 v[6:9], v[10:13], v[186:189], v[42:45]
	v_mfma_i32_16x16x64_i8 v[6:9], v[14:17], v[190:193], v[6:9]
	v_mfma_i32_16x16x64_i8 v[42:45], v[18:21], v[150:153], v[70:73]
	v_mfma_i32_16x16x64_i8 v[70:73], v[22:25], v[162:165], v[42:45]
	v_mfma_i32_16x16x64_i8 v[42:45], v[26:29], v[150:153], v[66:69]
	v_mfma_i32_16x16x64_i8 v[66:69], v[30:33], v[162:165], v[42:45]
	v_mfma_i32_16x16x64_i8 v[42:45], v[18:21], v[178:181], v[54:57]
	v_mfma_i32_16x16x64_i8 v[10:13], v[18:21], v[134:137], v[86:89]
	v_mfma_i32_16x16x64_i8 v[54:57], v[22:25], v[182:185], v[42:45]
	v_mfma_i32_16x16x64_i8 v[42:45], v[26:29], v[178:181], v[50:53]
	v_mfma_i32_16x16x64_i8 v[18:21], v[18:21], v[186:189], v[38:41]
	v_mfma_i32_16x16x64_i8 v[10:13], v[22:25], v[146:149], v[10:13]
	v_mfma_i32_16x16x64_i8 v[14:17], v[26:29], v[134:137], v[82:85]
	v_mfma_i32_16x16x64_i8 v[50:53], v[30:33], v[182:185], v[42:45]
	v_mfma_i32_16x16x64_i8 v[18:21], v[22:25], v[190:193], v[18:21]
	v_mfma_i32_16x16x64_i8 v[22:25], v[26:29], v[186:189], v[34:37]
	v_mfma_i32_16x16x64_i8 v[14:17], v[30:33], v[146:149], v[14:17]
	v_mfma_i32_16x16x64_i8 v[22:25], v[30:33], v[190:193], v[22:25]
	s_barrier
	s_add_i32 s81, 0, 0x18000
	s_add_i32 s82, 0, 0x1c000
	v_add_u32_e32 v38, s81, v229
	v_add_u32_e32 v42, s82, v229
	ds_read_b128 v[26:29], v38
	ds_read_b128 v[30:33], v38 offset:1024
	ds_read_b128 v[34:37], v38 offset:2048
	ds_read_b128 v[38:41], v38 offset:3072
	ds_read_b128 v[178:181], v42
	ds_read_b128 v[182:185], v42 offset:1024
	ds_read_b128 v[186:189], v42 offset:2048
	ds_read_b128 v[190:193], v42 offset:3072
	s_add_u32 s8, s8, 0x80000
	s_addc_u32 s9, s9, 0
	s_mov_b32 m0, s60
	v_lshl_add_u64 v[134:135], s[8:9], 0, v[196:197]
	ds_read_b128 v[42:45], v236 offset:32768
	ds_read_b128 v[46:49], v236 offset:33792
	ds_read_b128 v[82:85], v236 offset:34816
	ds_read_b128 v[86:89], v236 offset:35840
	ds_read_b128 v[214:217], v236 offset:36864
	ds_read_b128 v[218:221], v236 offset:37888
	ds_read_b128 v[222:225], v236 offset:38912
	ds_read_b128 v[240:243], v236 offset:39936
	global_load_lds_dwordx4 v[134:135], off
	v_lshl_add_u64 v[134:135], s[8:9], 0, v[198:199]
	s_mov_b32 m0, s61
	s_nop 0
	global_load_lds_dwordx4 v[134:135], off
	s_waitcnt vmcnt(8)
	s_waitcnt lgkmcnt(0)
	s_barrier
	v_mfma_i32_16x16x64_i8 v[134:137], v[26:29], v[42:45], v[174:177]
	v_mfma_i32_16x16x64_i8 v[174:177], v[30:33], v[46:49], v[134:137]
	v_mfma_i32_16x16x64_i8 v[134:137], v[34:37], v[42:45], v[170:173]
	v_mfma_i32_16x16x64_i8 v[170:173], v[38:41], v[46:49], v[134:137]
	v_mfma_i32_16x16x64_i8 v[134:137], v[26:29], v[82:85], v[158:161]
	v_mfma_i32_16x16x64_i8 v[158:161], v[30:33], v[86:89], v[134:137]
	v_mfma_i32_16x16x64_i8 v[134:137], v[34:37], v[82:85], v[154:157]
	v_mfma_i32_16x16x64_i8 v[154:157], v[38:41], v[86:89], v[134:137]
	v_mfma_i32_16x16x64_i8 v[134:137], v[26:29], v[214:217], v[142:145]
	v_mfma_i32_16x16x64_i8 v[142:145], v[30:33], v[218:221], v[134:137]
	v_mfma_i32_16x16x64_i8 v[134:137], v[34:37], v[214:217], v[138:141]
	v_mfma_i32_16x16x64_i8 v[126:129], v[26:29], v[222:225], v[126:129]
	v_mfma_i32_16x16x64_i8 v[122:125], v[34:37], v[222:225], v[122:125]
	v_mfma_i32_16x16x64_i8 v[138:141], v[38:41], v[218:221], v[134:137]
	v_mfma_i32_16x16x64_i8 v[126:129], v[30:33], v[240:243], v[126:129]
	v_mfma_i32_16x16x64_i8 v[122:125], v[38:41], v[240:243], v[122:125]
	v_mfma_i32_16x16x64_i8 v[134:137], v[178:181], v[42:45], v[166:169]
	v_mfma_i32_16x16x64_i8 v[42:45], v[186:189], v[42:45], v[98:101]
	v_mfma_i32_16x16x64_i8 v[162:165], v[190:193], v[46:49], v[42:45]
	v_mfma_i32_16x16x64_i8 v[42:45], v[178:181], v[82:85], v[102:105]
	v_mfma_i32_16x16x64_i8 v[150:153], v[182:185], v[86:89], v[42:45]
	v_mfma_i32_16x16x64_i8 v[42:45], v[186:189], v[82:85], v[106:109]
	v_mfma_i32_16x16x64_i8 v[146:149], v[190:193], v[86:89], v[42:45]
	v_mfma_i32_16x16x64_i8 v[42:45], v[178:181], v[214:217], v[110:113]
	v_mfma_i32_16x16x64_i8 v[166:169], v[182:185], v[46:49], v[134:137]
	v_mfma_i32_16x16x64_i8 v[134:137], v[182:185], v[218:221], v[42:45]
	v_mfma_i32_16x16x64_i8 v[42:45], v[186:189], v[214:217], v[130:133]
	v_mfma_i32_16x16x64_i8 v[130:133], v[190:193], v[218:221], v[42:45]
	v_mfma_i32_16x16x64_i8 v[42:45], v[178:181], v[222:225], v[118:121]
	v_mfma_i32_16x16x64_i8 v[118:121], v[182:185], v[240:243], v[42:45]
	v_mfma_i32_16x16x64_i8 v[42:45], v[186:189], v[222:225], v[114:117]
	v_mfma_i32_16x16x64_i8 v[114:117], v[190:193], v[240:243], v[42:45]
	s_barrier
	s_add_i32 s8, s81, s41
	s_nop 3
	v_lshl_add_u64 v[42:43], v[226:227], 0, s[24:25]
	s_mov_b32 m0, s8
	ds_read_b128 v[82:85], v236 offset:49152
	ds_read_b128 v[98:101], v236 offset:50176
	ds_read_b128 v[102:105], v236 offset:51200
	ds_read_b128 v[106:109], v236 offset:52224
	ds_read_b128 v[110:113], v236 offset:53248
	ds_read_b128 v[214:217], v236 offset:54272
	ds_read_b128 v[218:221], v236 offset:55296
	ds_read_b128 v[222:225], v236 offset:56320
	global_load_lds_dwordx4 v[42:43], off
	s_add_i32 m0, s8, 0x2000
	s_add_u32 s6, s6, 0x80080
	v_lshl_add_u64 v[42:43], v[244:245], 0, s[24:25]
	s_addc_u32 s7, s7, 0
	s_add_i32 s8, s82, s41
	global_load_lds_dwordx4 v[42:43], off
	v_lshl_add_u64 v[42:43], s[6:7], 0, v[196:197]
	s_mov_b32 m0, s8
	s_nop 0
	global_load_lds_dwordx4 v[42:43], off
	v_lshl_add_u64 v[42:43], s[6:7], 0, v[198:199]
	s_add_i32 m0, s8, 0x2000
	s_nop 0
	global_load_lds_dwordx4 v[42:43], off
	v_lshl_add_u64 v[42:43], v[246:247], 0, s[24:25]
	s_mov_b32 m0, s63
	s_nop 0
	global_load_lds_dwordx4 v[42:43], off
	v_lshl_add_u64 v[42:43], v[248:249], 0, s[24:25]
	s_mov_b32 m0, s64
	s_nop 0
	global_load_lds_dwordx4 v[42:43], off
	s_waitcnt vmcnt(8)
	s_waitcnt lgkmcnt(0)
	s_barrier
	v_mfma_i32_16x16x64_i8 v[42:45], v[26:29], v[82:85], v[94:97]
	v_mfma_i32_16x16x64_i8 v[94:97], v[30:33], v[98:101], v[42:45]
	v_mfma_i32_16x16x64_i8 v[42:45], v[34:37], v[82:85], v[90:93]
	v_mfma_i32_16x16x64_i8 v[90:93], v[38:41], v[98:101], v[42:45]
	v_mfma_i32_16x16x64_i8 v[42:45], v[26:29], v[102:105], v[78:81]
	v_mfma_i32_16x16x64_i8 v[78:81], v[30:33], v[106:109], v[42:45]
	v_mfma_i32_16x16x64_i8 v[42:45], v[34:37], v[102:105], v[74:77]
	v_mfma_i32_16x16x64_i8 v[74:77], v[38:41], v[106:109], v[42:45]
	v_mfma_i32_16x16x64_i8 v[42:45], v[26:29], v[110:113], v[62:65]
	v_mfma_i32_16x16x64_i8 v[2:5], v[26:29], v[218:221], v[2:5]
	v_mfma_i32_16x16x64_i8 v[62:65], v[30:33], v[214:217], v[42:45]
	v_mfma_i32_16x16x64_i8 v[42:45], v[34:37], v[110:113], v[58:61]
	v_mfma_i32_16x16x64_i8 v[46:49], v[30:33], v[222:225], v[2:5]
	v_mfma_i32_16x16x64_i8 v[2:5], v[34:37], v[218:221], v[6:9]
	v_mfma_i32_16x16x64_i8 v[58:61], v[38:41], v[214:217], v[42:45]
	v_mfma_i32_16x16x64_i8 v[42:45], v[38:41], v[222:225], v[2:5]
	v_mfma_i32_16x16x64_i8 v[2:5], v[178:181], v[82:85], v[10:13]
	v_mfma_i32_16x16x64_i8 v[86:89], v[182:185], v[98:101], v[2:5]
	v_mfma_i32_16x16x64_i8 v[2:5], v[186:189], v[82:85], v[14:17]
	v_mfma_i32_16x16x64_i8 v[82:85], v[190:193], v[98:101], v[2:5]
	v_mfma_i32_16x16x64_i8 v[2:5], v[178:181], v[102:105], v[70:73]
	v_mfma_i32_16x16x64_i8 v[70:73], v[182:185], v[106:109], v[2:5]
	v_mfma_i32_16x16x64_i8 v[2:5], v[186:189], v[102:105], v[66:69]
	v_mfma_i32_16x16x64_i8 v[66:69], v[190:193], v[106:109], v[2:5]
	v_mfma_i32_16x16x64_i8 v[2:5], v[178:181], v[110:113], v[54:57]
	v_mfma_i32_16x16x64_i8 v[54:57], v[182:185], v[214:217], v[2:5]
	v_mfma_i32_16x16x64_i8 v[2:5], v[186:189], v[110:113], v[50:53]
	v_mfma_i32_16x16x64_i8 v[50:53], v[190:193], v[214:217], v[2:5]
	v_mfma_i32_16x16x64_i8 v[2:5], v[178:181], v[218:221], v[18:21]
	v_mfma_i32_16x16x64_i8 v[38:41], v[182:185], v[222:225], v[2:5]
	v_mfma_i32_16x16x64_i8 v[2:5], v[186:189], v[218:221], v[22:25]
	v_mfma_i32_16x16x64_i8 v[34:37], v[190:193], v[222:225], v[2:5]
	s_barrier
	s_add_i32 s80, s80, 2
	s_add_u32 s4, s4, 0x100
	s_addc_u32 s5, s5, 0
	s_add_u32 s78, s78, 0x100
	s_addc_u32 s79, s79, 0
	s_cmp_gt_u32 s80, 29
	s_cbranch_scc0 .LBB0_304
	s_and_b64 vcc, exec, s[12:13]
	s_cbranch_vccz .LBB0_307
	s_barrier

.LBB0_1232:
	ds_read_b128 v[106:109], v197
	ds_read_b128 v[114:117], v197 offset:1024
	ds_read_b128 v[122:125], v197 offset:2048
	ds_read_b128 v[130:133], v197 offset:3072
	ds_read_b128 v[146:149], v201
	ds_read_b128 v[150:153], v201 offset:1024
	ds_read_b128 v[154:157], v201 offset:2048
	ds_read_b128 v[158:161], v201 offset:3072
	s_add_u32 s30, s28, 0xfff80080
	s_addc_u32 s31, s29, -1
	s_cmp_eq_u32 s70, 28
	s_cselect_b32 s35, s23, s31
	s_cselect_b32 s34, s66, s30
	s_cselect_b32 s31, s15, s69
	s_cselect_b32 s30, s67, s68
	v_lshl_add_u64 v[194:195], s[28:29], 0, v[174:175]
	s_add_i32 m0, s19, 0xc000
	ds_read_b128 v[162:165], v204
	ds_read_b128 v[182:185], v204 offset:1024
	ds_read_b128 v[186:189], v204 offset:2048
	ds_read_b128 v[206:209], v204 offset:3072
	ds_read_b128 v[210:213], v204 offset:4096
	ds_read_b128 v[214:217], v204 offset:5120
	ds_read_b128 v[218:221], v204 offset:6144
	ds_read_b128 v[222:225], v204 offset:7168
	global_load_lds_dwordx4 v[194:195], off
	v_lshl_add_u64 v[194:195], s[28:29], 0, v[176:177]
	s_add_i32 m0, s19, 0xe000
	s_nop 0
	global_load_lds_dwordx4 v[194:195], off
	s_waitcnt vmcnt(8)
	s_waitcnt lgkmcnt(0)
	s_barrier
	v_mfma_i32_16x16x64_i8 v[142:145], v[106:109], v[162:165], v[142:145]
	v_mfma_i32_16x16x64_i8 v[138:141], v[122:125], v[162:165], v[138:141]
	v_mfma_i32_16x16x64_i8 v[118:121], v[106:109], v[186:189], v[118:121]
	v_mfma_i32_16x16x64_i8 v[110:113], v[122:125], v[186:189], v[110:113]
	v_mfma_i32_16x16x64_i8 v[94:97], v[106:109], v[210:213], v[94:97]
	v_mfma_i32_16x16x64_i8 v[90:93], v[122:125], v[210:213], v[90:93]
	v_mfma_i32_16x16x64_i8 v[78:81], v[106:109], v[218:221], v[78:81]
	v_mfma_i32_16x16x64_i8 v[74:77], v[122:125], v[218:221], v[74:77]
	v_mfma_i32_16x16x64_i8 v[142:145], v[114:117], v[182:185], v[142:145]
	v_mfma_i32_16x16x64_i8 v[138:141], v[130:133], v[182:185], v[138:141]
	v_mfma_i32_16x16x64_i8 v[118:121], v[114:117], v[206:209], v[118:121]
	v_mfma_i32_16x16x64_i8 v[110:113], v[130:133], v[206:209], v[110:113]
	v_mfma_i32_16x16x64_i8 v[94:97], v[114:117], v[214:217], v[94:97]
	v_mfma_i32_16x16x64_i8 v[90:93], v[130:133], v[214:217], v[90:93]
	v_mfma_i32_16x16x64_i8 v[78:81], v[114:117], v[222:225], v[78:81]
	v_mfma_i32_16x16x64_i8 v[74:77], v[130:133], v[222:225], v[74:77]
	v_mfma_i32_16x16x64_i8 v[134:137], v[146:149], v[162:165], v[134:137]
	v_mfma_i32_16x16x64_i8 v[126:129], v[154:157], v[162:165], v[126:129]
	v_mfma_i32_16x16x64_i8 v[102:105], v[146:149], v[186:189], v[102:105]
	v_mfma_i32_16x16x64_i8 v[98:101], v[154:157], v[186:189], v[98:101]
	v_mfma_i32_16x16x64_i8 v[86:89], v[146:149], v[210:213], v[86:89]
	v_mfma_i32_16x16x64_i8 v[82:85], v[154:157], v[210:213], v[82:85]
	v_mfma_i32_16x16x64_i8 v[70:73], v[146:149], v[218:221], v[70:73]
	v_mfma_i32_16x16x64_i8 v[66:69], v[154:157], v[218:221], v[66:69]
	v_mfma_i32_16x16x64_i8 v[134:137], v[150:153], v[182:185], v[134:137]
	v_mfma_i32_16x16x64_i8 v[126:129], v[158:161], v[182:185], v[126:129]
	v_mfma_i32_16x16x64_i8 v[102:105], v[150:153], v[206:209], v[102:105]
	v_mfma_i32_16x16x64_i8 v[98:101], v[158:161], v[206:209], v[98:101]
	v_mfma_i32_16x16x64_i8 v[86:89], v[150:153], v[214:217], v[86:89]
	v_mfma_i32_16x16x64_i8 v[82:85], v[158:161], v[214:217], v[82:85]
	v_mfma_i32_16x16x64_i8 v[70:73], v[150:153], v[222:225], v[70:73]
	v_mfma_i32_16x16x64_i8 v[66:69], v[158:161], v[222:225], v[66:69]
	s_barrier
	s_add_i32 s71, s63, s39
	v_lshl_add_u64 v[194:195], s[30:31], 0, v[168:169]
	s_mov_b32 m0, s71
	ds_read_b128 v[162:165], v204 offset:16384
	ds_read_b128 v[182:185], v204 offset:17408
	ds_read_b128 v[186:189], v204 offset:18432
	ds_read_b128 v[206:209], v204 offset:19456
	ds_read_b128 v[210:213], v204 offset:20480
	ds_read_b128 v[214:217], v204 offset:21504
	ds_read_b128 v[218:221], v204 offset:22528
	ds_read_b128 v[222:225], v204 offset:23552
	global_load_lds_dwordx4 v[194:195], off
	s_add_i32 m0, s71, 0x2000
	s_add_u32 s72, s30, 0x80000
	v_lshl_add_u64 v[198:199], s[30:31], 0, v[172:173]
	s_addc_u32 s73, s31, 0
	s_add_i32 s71, s64, s39
	global_load_lds_dwordx4 v[198:199], off
	v_lshl_add_u64 v[202:203], s[72:73], 0, v[168:169]
	s_mov_b32 m0, s71
	v_lshl_add_u64 v[226:227], s[34:35], 0, v[170:171]
	global_load_lds_dwordx4 v[202:203], off
	v_lshl_add_u64 v[202:203], s[72:73], 0, v[172:173]
	s_add_i32 m0, s71, 0x2000
	s_nop 0
	global_load_lds_dwordx4 v[202:203], off
	v_lshl_add_u64 v[202:203], s[34:35], 0, v[166:167]
	s_mov_b32 m0, s19
	s_nop 0
	global_load_lds_dwordx4 v[202:203], off
	s_mov_b32 m0, s40
	s_nop 0
	global_load_lds_dwordx4 v[226:227], off
	s_waitcnt vmcnt(8)
	s_waitcnt lgkmcnt(0)
	s_barrier
	v_mfma_i32_16x16x64_i8 v[62:65], v[106:109], v[162:165], v[62:65]
	v_mfma_i32_16x16x64_i8 v[58:61], v[122:125], v[162:165], v[58:61]
	v_mfma_i32_16x16x64_i8 v[46:49], v[106:109], v[186:189], v[46:49]
	v_mfma_i32_16x16x64_i8 v[42:45], v[122:125], v[186:189], v[42:45]
	v_mfma_i32_16x16x64_i8 v[30:33], v[106:109], v[210:213], v[30:33]
	v_mfma_i32_16x16x64_i8 v[26:29], v[122:125], v[210:213], v[26:29]
	v_mfma_i32_16x16x64_i8 v[14:17], v[106:109], v[218:221], v[14:17]
	v_mfma_i32_16x16x64_i8 v[10:13], v[122:125], v[218:221], v[10:13]
	v_mfma_i32_16x16x64_i8 v[62:65], v[114:117], v[182:185], v[62:65]
	v_mfma_i32_16x16x64_i8 v[58:61], v[130:133], v[182:185], v[58:61]
	v_mfma_i32_16x16x64_i8 v[46:49], v[114:117], v[206:209], v[46:49]
	v_mfma_i32_16x16x64_i8 v[42:45], v[130:133], v[206:209], v[42:45]
	v_mfma_i32_16x16x64_i8 v[30:33], v[114:117], v[214:217], v[30:33]
	v_mfma_i32_16x16x64_i8 v[26:29], v[130:133], v[214:217], v[26:29]
	v_mfma_i32_16x16x64_i8 v[14:17], v[114:117], v[222:225], v[14:17]
	v_mfma_i32_16x16x64_i8 v[10:13], v[130:133], v[222:225], v[10:13]
	v_mfma_i32_16x16x64_i8 v[54:57], v[146:149], v[162:165], v[54:57]
	v_mfma_i32_16x16x64_i8 v[50:53], v[154:157], v[162:165], v[50:53]
	v_mfma_i32_16x16x64_i8 v[38:41], v[146:149], v[186:189], v[38:41]
	v_mfma_i32_16x16x64_i8 v[34:37], v[154:157], v[186:189], v[34:37]
	v_mfma_i32_16x16x64_i8 v[22:25], v[146:149], v[210:213], v[22:25]
	v_mfma_i32_16x16x64_i8 v[18:21], v[154:157], v[210:213], v[18:21]
	v_mfma_i32_16x16x64_i8 v[6:9], v[146:149], v[218:221], v[6:9]
	v_mfma_i32_16x16x64_i8 v[2:5], v[154:157], v[218:221], v[2:5]
	v_mfma_i32_16x16x64_i8 v[54:57], v[150:153], v[182:185], v[54:57]
	v_mfma_i32_16x16x64_i8 v[50:53], v[158:161], v[182:185], v[50:53]
	v_mfma_i32_16x16x64_i8 v[38:41], v[150:153], v[206:209], v[38:41]
	v_mfma_i32_16x16x64_i8 v[34:37], v[158:161], v[206:209], v[34:37]
	v_mfma_i32_16x16x64_i8 v[22:25], v[150:153], v[214:217], v[22:25]
	v_mfma_i32_16x16x64_i8 v[18:21], v[158:161], v[214:217], v[18:21]
	v_mfma_i32_16x16x64_i8 v[6:9], v[150:153], v[222:225], v[6:9]
	v_mfma_i32_16x16x64_i8 v[2:5], v[158:161], v[222:225], v[2:5]
	s_barrier
	s_add_i32 s71, 0, 0x18000
	s_add_i32 s72, 0, 0x1c000
	v_add_u32_e32 v130, s71, v193
	v_add_u32_e32 v158, s72, v193
	ds_read_b128 v[106:109], v130
	ds_read_b128 v[114:117], v130 offset:1024
	ds_read_b128 v[122:125], v130 offset:2048
	ds_read_b128 v[130:133], v130 offset:3072
	ds_read_b128 v[146:149], v158
	ds_read_b128 v[150:153], v158 offset:1024
	ds_read_b128 v[154:157], v158 offset:2048
	ds_read_b128 v[158:161], v158 offset:3072
	s_add_u32 s34, s34, 0x80000
	s_addc_u32 s35, s35, 0
	s_mov_b32 m0, s41
	v_lshl_add_u64 v[228:229], s[34:35], 0, v[166:167]
	ds_read_b128 v[162:165], v204 offset:32768
	ds_read_b128 v[182:185], v204 offset:33792
	ds_read_b128 v[186:189], v204 offset:34816
	ds_read_b128 v[206:209], v204 offset:35840
	ds_read_b128 v[210:213], v204 offset:36864
	ds_read_b128 v[214:217], v204 offset:37888
	ds_read_b128 v[218:221], v204 offset:38912
	ds_read_b128 v[222:225], v204 offset:39936
	global_load_lds_dwordx4 v[228:229], off
	v_lshl_add_u64 v[228:229], s[34:35], 0, v[170:171]
	s_mov_b32 m0, s42
	s_nop 0
	global_load_lds_dwordx4 v[228:229], off
	s_waitcnt vmcnt(8)
	s_waitcnt lgkmcnt(0)
	s_barrier
	v_mfma_i32_16x16x64_i8 v[142:145], v[106:109], v[162:165], v[142:145]
	v_mfma_i32_16x16x64_i8 v[138:141], v[122:125], v[162:165], v[138:141]
	v_mfma_i32_16x16x64_i8 v[118:121], v[106:109], v[186:189], v[118:121]
	v_mfma_i32_16x16x64_i8 v[110:113], v[122:125], v[186:189], v[110:113]
	v_mfma_i32_16x16x64_i8 v[94:97], v[106:109], v[210:213], v[94:97]
	v_mfma_i32_16x16x64_i8 v[90:93], v[122:125], v[210:213], v[90:93]
	v_mfma_i32_16x16x64_i8 v[78:81], v[106:109], v[218:221], v[78:81]
	v_mfma_i32_16x16x64_i8 v[74:77], v[122:125], v[218:221], v[74:77]
	v_mfma_i32_16x16x64_i8 v[142:145], v[114:117], v[182:185], v[142:145]
	v_mfma_i32_16x16x64_i8 v[138:141], v[130:133], v[182:185], v[138:141]
	v_mfma_i32_16x16x64_i8 v[118:121], v[114:117], v[206:209], v[118:121]
	v_mfma_i32_16x16x64_i8 v[110:113], v[130:133], v[206:209], v[110:113]
	v_mfma_i32_16x16x64_i8 v[94:97], v[114:117], v[214:217], v[94:97]
	v_mfma_i32_16x16x64_i8 v[90:93], v[130:133], v[214:217], v[90:93]
	v_mfma_i32_16x16x64_i8 v[78:81], v[114:117], v[222:225], v[78:81]
	v_mfma_i32_16x16x64_i8 v[74:77], v[130:133], v[222:225], v[74:77]
	v_mfma_i32_16x16x64_i8 v[134:137], v[146:149], v[162:165], v[134:137]
	v_mfma_i32_16x16x64_i8 v[126:129], v[154:157], v[162:165], v[126:129]
	v_mfma_i32_16x16x64_i8 v[102:105], v[146:149], v[186:189], v[102:105]
	v_mfma_i32_16x16x64_i8 v[98:101], v[154:157], v[186:189], v[98:101]
	v_mfma_i32_16x16x64_i8 v[86:89], v[146:149], v[210:213], v[86:89]
	v_mfma_i32_16x16x64_i8 v[82:85], v[154:157], v[210:213], v[82:85]
	v_mfma_i32_16x16x64_i8 v[70:73], v[146:149], v[218:221], v[70:73]
	v_mfma_i32_16x16x64_i8 v[66:69], v[154:157], v[218:221], v[66:69]
	v_mfma_i32_16x16x64_i8 v[134:137], v[150:153], v[182:185], v[134:137]
	v_mfma_i32_16x16x64_i8 v[126:129], v[158:161], v[182:185], v[126:129]
	v_mfma_i32_16x16x64_i8 v[102:105], v[150:153], v[206:209], v[102:105]
	v_mfma_i32_16x16x64_i8 v[98:101], v[158:161], v[206:209], v[98:101]
	v_mfma_i32_16x16x64_i8 v[86:89], v[150:153], v[214:217], v[86:89]
	v_mfma_i32_16x16x64_i8 v[82:85], v[158:161], v[214:217], v[82:85]
	v_mfma_i32_16x16x64_i8 v[70:73], v[150:153], v[222:225], v[70:73]
	v_mfma_i32_16x16x64_i8 v[66:69], v[158:161], v[222:225], v[66:69]
	s_barrier
	s_add_i32 s34, s71, s39
	v_lshl_add_u64 v[194:195], v[194:195], 0, s[10:11]
	s_mov_b32 m0, s34
	ds_read_b128 v[162:165], v204 offset:49152
	ds_read_b128 v[182:185], v204 offset:50176
	ds_read_b128 v[186:189], v204 offset:51200
	ds_read_b128 v[206:209], v204 offset:52224
	ds_read_b128 v[210:213], v204 offset:53248
	ds_read_b128 v[214:217], v204 offset:54272
	ds_read_b128 v[218:221], v204 offset:55296
	ds_read_b128 v[222:225], v204 offset:56320
	global_load_lds_dwordx4 v[194:195], off
	s_add_i32 m0, s34, 0x2000
	s_add_u32 s30, s30, 0x80080
	v_lshl_add_u64 v[194:195], v[198:199], 0, s[10:11]
	s_addc_u32 s31, s31, 0
	s_add_i32 s34, s72, s39
	global_load_lds_dwordx4 v[194:195], off
	v_lshl_add_u64 v[194:195], s[30:31], 0, v[168:169]
	s_mov_b32 m0, s34
	s_nop 0
	global_load_lds_dwordx4 v[194:195], off
	v_lshl_add_u64 v[194:195], s[30:31], 0, v[172:173]
	s_add_i32 m0, s34, 0x2000
	s_nop 0
	global_load_lds_dwordx4 v[194:195], off
	v_lshl_add_u64 v[194:195], v[202:203], 0, s[10:11]
	s_mov_b32 m0, s60
	s_nop 0
	global_load_lds_dwordx4 v[194:195], off
	v_lshl_add_u64 v[194:195], v[226:227], 0, s[10:11]
	s_mov_b32 m0, s61
	s_nop 0
	global_load_lds_dwordx4 v[194:195], off
	s_waitcnt vmcnt(8)
	s_waitcnt lgkmcnt(0)
	s_barrier
	v_mfma_i32_16x16x64_i8 v[62:65], v[106:109], v[162:165], v[62:65]
	v_mfma_i32_16x16x64_i8 v[58:61], v[122:125], v[162:165], v[58:61]
	v_mfma_i32_16x16x64_i8 v[46:49], v[106:109], v[186:189], v[46:49]
	v_mfma_i32_16x16x64_i8 v[42:45], v[122:125], v[186:189], v[42:45]
	v_mfma_i32_16x16x64_i8 v[30:33], v[106:109], v[210:213], v[30:33]
	v_mfma_i32_16x16x64_i8 v[26:29], v[122:125], v[210:213], v[26:29]
	v_mfma_i32_16x16x64_i8 v[14:17], v[106:109], v[218:221], v[14:17]
	v_mfma_i32_16x16x64_i8 v[10:13], v[122:125], v[218:221], v[10:13]
	v_mfma_i32_16x16x64_i8 v[62:65], v[114:117], v[182:185], v[62:65]
	v_mfma_i32_16x16x64_i8 v[58:61], v[130:133], v[182:185], v[58:61]
	v_mfma_i32_16x16x64_i8 v[46:49], v[114:117], v[206:209], v[46:49]
	v_mfma_i32_16x16x64_i8 v[42:45], v[130:133], v[206:209], v[42:45]
	v_mfma_i32_16x16x64_i8 v[30:33], v[114:117], v[214:217], v[30:33]
	v_mfma_i32_16x16x64_i8 v[26:29], v[130:133], v[214:217], v[26:29]
	v_mfma_i32_16x16x64_i8 v[14:17], v[114:117], v[222:225], v[14:17]
	v_mfma_i32_16x16x64_i8 v[10:13], v[130:133], v[222:225], v[10:13]
	v_mfma_i32_16x16x64_i8 v[54:57], v[146:149], v[162:165], v[54:57]
	v_mfma_i32_16x16x64_i8 v[50:53], v[154:157], v[162:165], v[50:53]
	v_mfma_i32_16x16x64_i8 v[38:41], v[146:149], v[186:189], v[38:41]
	v_mfma_i32_16x16x64_i8 v[34:37], v[154:157], v[186:189], v[34:37]
	v_mfma_i32_16x16x64_i8 v[22:25], v[146:149], v[210:213], v[22:25]
	v_mfma_i32_16x16x64_i8 v[18:21], v[154:157], v[210:213], v[18:21]
	v_mfma_i32_16x16x64_i8 v[6:9], v[146:149], v[218:221], v[6:9]
	v_mfma_i32_16x16x64_i8 v[2:5], v[154:157], v[218:221], v[2:5]
	v_mfma_i32_16x16x64_i8 v[54:57], v[150:153], v[182:185], v[54:57]
	v_mfma_i32_16x16x64_i8 v[50:53], v[158:161], v[182:185], v[50:53]
	v_mfma_i32_16x16x64_i8 v[38:41], v[150:153], v[206:209], v[38:41]
	v_mfma_i32_16x16x64_i8 v[34:37], v[158:161], v[206:209], v[34:37]
	v_mfma_i32_16x16x64_i8 v[22:25], v[150:153], v[214:217], v[22:25]
	v_mfma_i32_16x16x64_i8 v[18:21], v[158:161], v[214:217], v[18:21]
	v_mfma_i32_16x16x64_i8 v[6:9], v[150:153], v[222:225], v[6:9]
	v_mfma_i32_16x16x64_i8 v[2:5], v[158:161], v[222:225], v[2:5]
	s_barrier
	s_add_i32 s70, s70, 2
	s_add_u32 s28, s28, 0x100
	s_addc_u32 s29, s29, 0
	s_add_u32 s68, s68, 0x100
	s_addc_u32 s69, s69, 0
	s_cmp_gt_u32 s70, 29
	s_cbranch_scc0 .LBB0_1232
	s_and_b64 vcc, exec, s[12:13]
	s_cbranch_vccz .LBB0_1235
	s_barrier

.LBB0_1367:
	ds_read_b128 v[130:133], v234
	ds_read_b128 v[134:137], v234 offset:1024
	ds_read_b128 v[162:165], v234 offset:2048
	ds_read_b128 v[166:169], v234 offset:3072
	ds_read_b128 v[170:173], v235
	ds_read_b128 v[174:177], v235 offset:1024
	ds_read_b128 v[178:181], v235 offset:2048
	ds_read_b128 v[182:185], v235 offset:3072
	s_add_u32 s6, s4, 0x100
	s_addc_u32 s7, s5, 0
	s_cmp_eq_u32 s80, 28
	s_cselect_b32 s57, s35, s7
	s_cselect_b32 s56, s43, s6
	s_cselect_b32 s19, s31, s79
	s_cselect_b32 s18, vcc_lo, vcc_hi
	v_lshl_add_u64 v[218:219], s[4:5], 0, v[154:155]
	s_add_i32 m0, s65, 0xc000
	ds_read_b128 v[186:189], v236
	ds_read_b128 v[190:193], v236 offset:1024
	ds_read_b128 v[194:197], v236 offset:2048
	ds_read_b128 v[198:201], v236 offset:3072
	ds_read_b128 v[202:205], v236 offset:4096
	ds_read_b128 v[206:209], v236 offset:5120
	ds_read_b128 v[210:213], v236 offset:6144
	ds_read_b128 v[214:217], v236 offset:7168
	global_load_lds_dwordx4 v[218:219], off
	v_lshl_add_u64 v[218:219], s[4:5], 0, v[156:157]
	s_add_i32 m0, s65, 0xe000
	s_nop 0
	global_load_lds_dwordx4 v[218:219], off
	s_waitcnt vmcnt(8)
	s_waitcnt lgkmcnt(0)
	s_barrier
	v_mfma_i32_16x16x64_i8 v[118:121], v[130:133], v[186:189], v[118:121]
	v_mfma_i32_16x16x64_i8 v[102:105], v[162:165], v[186:189], v[102:105]
	v_mfma_i32_16x16x64_i8 v[114:117], v[130:133], v[194:197], v[114:117]
	v_mfma_i32_16x16x64_i8 v[98:101], v[162:165], v[194:197], v[98:101]
	v_mfma_i32_16x16x64_i8 v[126:129], v[130:133], v[202:205], v[126:129]
	v_mfma_i32_16x16x64_i8 v[110:113], v[162:165], v[202:205], v[110:113]
	v_mfma_i32_16x16x64_i8 v[122:125], v[130:133], v[210:213], v[122:125]
	v_mfma_i32_16x16x64_i8 v[106:109], v[162:165], v[210:213], v[106:109]
	v_mfma_i32_16x16x64_i8 v[118:121], v[134:137], v[190:193], v[118:121]
	v_mfma_i32_16x16x64_i8 v[102:105], v[166:169], v[190:193], v[102:105]
	v_mfma_i32_16x16x64_i8 v[114:117], v[134:137], v[198:201], v[114:117]
	v_mfma_i32_16x16x64_i8 v[98:101], v[166:169], v[198:201], v[98:101]
	v_mfma_i32_16x16x64_i8 v[126:129], v[134:137], v[206:209], v[126:129]
	v_mfma_i32_16x16x64_i8 v[110:113], v[166:169], v[206:209], v[110:113]
	v_mfma_i32_16x16x64_i8 v[122:125], v[134:137], v[214:217], v[122:125]
	v_mfma_i32_16x16x64_i8 v[106:109], v[166:169], v[214:217], v[106:109]
	v_mfma_i32_16x16x64_i8 v[86:89], v[170:173], v[186:189], v[86:89]
	v_mfma_i32_16x16x64_i8 v[70:73], v[178:181], v[186:189], v[70:73]
	v_mfma_i32_16x16x64_i8 v[82:85], v[170:173], v[194:197], v[82:85]
	v_mfma_i32_16x16x64_i8 v[66:69], v[178:181], v[194:197], v[66:69]
	v_mfma_i32_16x16x64_i8 v[94:97], v[170:173], v[202:205], v[94:97]
	v_mfma_i32_16x16x64_i8 v[78:81], v[178:181], v[202:205], v[78:81]
	v_mfma_i32_16x16x64_i8 v[90:93], v[170:173], v[210:213], v[90:93]
	v_mfma_i32_16x16x64_i8 v[74:77], v[178:181], v[210:213], v[74:77]
	v_mfma_i32_16x16x64_i8 v[86:89], v[174:177], v[190:193], v[86:89]
	v_mfma_i32_16x16x64_i8 v[70:73], v[182:185], v[190:193], v[70:73]
	v_mfma_i32_16x16x64_i8 v[82:85], v[174:177], v[198:201], v[82:85]
	v_mfma_i32_16x16x64_i8 v[66:69], v[182:185], v[198:201], v[66:69]
	v_mfma_i32_16x16x64_i8 v[94:97], v[174:177], v[206:209], v[94:97]
	v_mfma_i32_16x16x64_i8 v[78:81], v[182:185], v[206:209], v[78:81]
	v_mfma_i32_16x16x64_i8 v[90:93], v[174:177], v[214:217], v[90:93]
	v_mfma_i32_16x16x64_i8 v[74:77], v[182:185], v[214:217], v[74:77]
	s_barrier
	s_add_i32 s4, s97, s63
	v_lshl_add_u64 v[218:219], s[18:19], 0, v[144:145]
	s_mov_b32 m0, s4
	ds_read_b128 v[186:189], v236 offset:16384
	ds_read_b128 v[190:193], v236 offset:17408
	ds_read_b128 v[194:197], v236 offset:18432
	ds_read_b128 v[198:201], v236 offset:19456
	ds_read_b128 v[202:205], v236 offset:20480
	ds_read_b128 v[206:209], v236 offset:21504
	ds_read_b128 v[210:213], v236 offset:22528
	ds_read_b128 v[214:217], v236 offset:23552
	global_load_lds_dwordx4 v[218:219], off
	s_add_i32 m0, s4, 0x2000
	s_add_u32 s4, s18, 0x80000
	v_lshl_add_u64 v[220:221], s[18:19], 0, v[148:149]
	s_addc_u32 s5, s19, 0
	s_add_i32 s81, s0, s63
	global_load_lds_dwordx4 v[220:221], off
	v_lshl_add_u64 v[222:223], s[4:5], 0, v[144:145]
	s_mov_b32 m0, s81
	v_lshl_add_u64 v[224:225], s[56:57], 0, v[146:147]
	global_load_lds_dwordx4 v[222:223], off
	v_lshl_add_u64 v[222:223], s[4:5], 0, v[148:149]
	s_add_i32 m0, s81, 0x2000
	s_nop 0
	global_load_lds_dwordx4 v[222:223], off
	v_lshl_add_u64 v[222:223], s[56:57], 0, v[142:143]
	s_mov_b32 m0, s65
	s_nop 0
	global_load_lds_dwordx4 v[222:223], off
	s_mov_b32 m0, s66
	s_nop 0
	global_load_lds_dwordx4 v[224:225], off
	s_waitcnt vmcnt(8)
	s_waitcnt lgkmcnt(0)
	s_barrier
	v_mfma_i32_16x16x64_i8 v[54:57], v[130:133], v[186:189], v[54:57]
	v_mfma_i32_16x16x64_i8 v[18:21], v[162:165], v[186:189], v[18:21]
	v_mfma_i32_16x16x64_i8 v[50:53], v[130:133], v[194:197], v[50:53]
	v_mfma_i32_16x16x64_i8 v[22:25], v[162:165], v[194:197], v[22:25]
	v_mfma_i32_16x16x64_i8 v[62:65], v[130:133], v[202:205], v[62:65]
	v_mfma_i32_16x16x64_i8 v[30:33], v[162:165], v[202:205], v[30:33]
	v_mfma_i32_16x16x64_i8 v[58:61], v[130:133], v[210:213], v[58:61]
	v_mfma_i32_16x16x64_i8 v[26:29], v[162:165], v[210:213], v[26:29]
	v_mfma_i32_16x16x64_i8 v[54:57], v[134:137], v[190:193], v[54:57]
	v_mfma_i32_16x16x64_i8 v[18:21], v[166:169], v[190:193], v[18:21]
	v_mfma_i32_16x16x64_i8 v[50:53], v[134:137], v[198:201], v[50:53]
	v_mfma_i32_16x16x64_i8 v[22:25], v[166:169], v[198:201], v[22:25]
	v_mfma_i32_16x16x64_i8 v[62:65], v[134:137], v[206:209], v[62:65]
	v_mfma_i32_16x16x64_i8 v[30:33], v[166:169], v[206:209], v[30:33]
	v_mfma_i32_16x16x64_i8 v[58:61], v[134:137], v[214:217], v[58:61]
	v_mfma_i32_16x16x64_i8 v[26:29], v[166:169], v[214:217], v[26:29]
	v_mfma_i32_16x16x64_i8 v[46:49], v[170:173], v[186:189], v[46:49]
	v_mfma_i32_16x16x64_i8 v[14:17], v[178:181], v[186:189], v[14:17]
	v_mfma_i32_16x16x64_i8 v[42:45], v[170:173], v[194:197], v[42:45]
	v_mfma_i32_16x16x64_i8 v[10:13], v[178:181], v[194:197], v[10:13]
	v_mfma_i32_16x16x64_i8 v[38:41], v[170:173], v[202:205], v[38:41]
	v_mfma_i32_16x16x64_i8 v[6:9], v[178:181], v[202:205], v[6:9]
	v_mfma_i32_16x16x64_i8 v[34:37], v[170:173], v[210:213], v[34:37]
	v_mfma_i32_16x16x64_i8 v[2:5], v[178:181], v[210:213], v[2:5]
	v_mfma_i32_16x16x64_i8 v[46:49], v[174:177], v[190:193], v[46:49]
	v_mfma_i32_16x16x64_i8 v[14:17], v[182:185], v[190:193], v[14:17]
	v_mfma_i32_16x16x64_i8 v[42:45], v[174:177], v[198:201], v[42:45]
	v_mfma_i32_16x16x64_i8 v[10:13], v[182:185], v[198:201], v[10:13]
	v_mfma_i32_16x16x64_i8 v[38:41], v[174:177], v[206:209], v[38:41]
	v_mfma_i32_16x16x64_i8 v[6:9], v[182:185], v[206:209], v[6:9]
	v_mfma_i32_16x16x64_i8 v[34:37], v[174:177], v[214:217], v[34:37]
	v_mfma_i32_16x16x64_i8 v[2:5], v[182:185], v[214:217], v[2:5]
	s_barrier
	s_add_i32 s81, 0, 0x18000
	s_add_i32 s82, 0, 0x1c000
	v_add_u32_e32 v166, s81, v232
	v_add_u32_e32 v182, s82, v232
	ds_read_b128 v[130:133], v166
	ds_read_b128 v[134:137], v166 offset:1024
	ds_read_b128 v[162:165], v166 offset:2048
	ds_read_b128 v[166:169], v166 offset:3072
	ds_read_b128 v[170:173], v182
	ds_read_b128 v[174:177], v182 offset:1024
	ds_read_b128 v[178:181], v182 offset:2048
	ds_read_b128 v[182:185], v182 offset:3072
	s_add_u32 s4, s56, 0x80000
	s_addc_u32 s5, s57, 0
	s_mov_b32 m0, s67
	v_lshl_add_u64 v[226:227], s[4:5], 0, v[142:143]
	ds_read_b128 v[186:189], v236 offset:32768
	ds_read_b128 v[190:193], v236 offset:33792
	ds_read_b128 v[194:197], v236 offset:34816
	ds_read_b128 v[198:201], v236 offset:35840
	ds_read_b128 v[202:205], v236 offset:36864
	ds_read_b128 v[206:209], v236 offset:37888
	ds_read_b128 v[210:213], v236 offset:38912
	ds_read_b128 v[214:217], v236 offset:39936
	global_load_lds_dwordx4 v[226:227], off
	v_lshl_add_u64 v[226:227], s[4:5], 0, v[146:147]
	s_mov_b32 m0, s68
	s_nop 0
	global_load_lds_dwordx4 v[226:227], off
	s_waitcnt vmcnt(8)
	s_waitcnt lgkmcnt(0)
	s_barrier
	v_mfma_i32_16x16x64_i8 v[118:121], v[130:133], v[186:189], v[118:121]
	v_mfma_i32_16x16x64_i8 v[102:105], v[162:165], v[186:189], v[102:105]
	v_mfma_i32_16x16x64_i8 v[114:117], v[130:133], v[194:197], v[114:117]
	v_mfma_i32_16x16x64_i8 v[98:101], v[162:165], v[194:197], v[98:101]
	v_mfma_i32_16x16x64_i8 v[126:129], v[130:133], v[202:205], v[126:129]
	v_mfma_i32_16x16x64_i8 v[110:113], v[162:165], v[202:205], v[110:113]
	v_mfma_i32_16x16x64_i8 v[122:125], v[130:133], v[210:213], v[122:125]
	v_mfma_i32_16x16x64_i8 v[106:109], v[162:165], v[210:213], v[106:109]
	v_mfma_i32_16x16x64_i8 v[118:121], v[134:137], v[190:193], v[118:121]
	v_mfma_i32_16x16x64_i8 v[102:105], v[166:169], v[190:193], v[102:105]
	v_mfma_i32_16x16x64_i8 v[114:117], v[134:137], v[198:201], v[114:117]
	v_mfma_i32_16x16x64_i8 v[98:101], v[166:169], v[198:201], v[98:101]
	v_mfma_i32_16x16x64_i8 v[126:129], v[134:137], v[206:209], v[126:129]
	v_mfma_i32_16x16x64_i8 v[110:113], v[166:169], v[206:209], v[110:113]
	v_mfma_i32_16x16x64_i8 v[122:125], v[134:137], v[214:217], v[122:125]
	v_mfma_i32_16x16x64_i8 v[106:109], v[166:169], v[214:217], v[106:109]
	v_mfma_i32_16x16x64_i8 v[86:89], v[170:173], v[186:189], v[86:89]
	v_mfma_i32_16x16x64_i8 v[70:73], v[178:181], v[186:189], v[70:73]
	v_mfma_i32_16x16x64_i8 v[82:85], v[170:173], v[194:197], v[82:85]
	v_mfma_i32_16x16x64_i8 v[66:69], v[178:181], v[194:197], v[66:69]
	v_mfma_i32_16x16x64_i8 v[94:97], v[170:173], v[202:205], v[94:97]
	v_mfma_i32_16x16x64_i8 v[78:81], v[178:181], v[202:205], v[78:81]
	v_mfma_i32_16x16x64_i8 v[90:93], v[170:173], v[210:213], v[90:93]
	v_mfma_i32_16x16x64_i8 v[74:77], v[178:181], v[210:213], v[74:77]
	v_mfma_i32_16x16x64_i8 v[86:89], v[174:177], v[190:193], v[86:89]
	v_mfma_i32_16x16x64_i8 v[70:73], v[182:185], v[190:193], v[70:73]
	v_mfma_i32_16x16x64_i8 v[82:85], v[174:177], v[198:201], v[82:85]
	v_mfma_i32_16x16x64_i8 v[66:69], v[182:185], v[198:201], v[66:69]
	v_mfma_i32_16x16x64_i8 v[94:97], v[174:177], v[206:209], v[94:97]
	v_mfma_i32_16x16x64_i8 v[78:81], v[182:185], v[206:209], v[78:81]
	v_mfma_i32_16x16x64_i8 v[90:93], v[174:177], v[214:217], v[90:93]
	v_mfma_i32_16x16x64_i8 v[74:77], v[182:185], v[214:217], v[74:77]
	s_barrier
	s_add_i32 s4, s81, s63
	v_lshl_add_u64 v[218:219], v[218:219], 0, s[22:23]
	s_mov_b32 m0, s4
	ds_read_b128 v[186:189], v236 offset:49152
	ds_read_b128 v[190:193], v236 offset:50176
	ds_read_b128 v[194:197], v236 offset:51200
	ds_read_b128 v[198:201], v236 offset:52224
	ds_read_b128 v[202:205], v236 offset:53248
	ds_read_b128 v[206:209], v236 offset:54272
	ds_read_b128 v[210:213], v236 offset:55296
	ds_read_b128 v[214:217], v236 offset:56320
	global_load_lds_dwordx4 v[218:219], off
	s_add_i32 m0, s4, 0x2000
	s_add_u32 s4, s18, 0x80080
	v_lshl_add_u64 v[218:219], v[220:221], 0, s[22:23]
	s_addc_u32 s5, s19, 0
	s_add_i32 s18, s82, s63
	global_load_lds_dwordx4 v[218:219], off
	v_lshl_add_u64 v[218:219], s[4:5], 0, v[144:145]
	s_mov_b32 m0, s18
	s_nop 0
	global_load_lds_dwordx4 v[218:219], off
	v_lshl_add_u64 v[218:219], s[4:5], 0, v[148:149]
	s_add_i32 m0, s18, 0x2000
	s_nop 0
	global_load_lds_dwordx4 v[218:219], off
	v_lshl_add_u64 v[218:219], v[222:223], 0, s[22:23]
	s_mov_b32 m0, s77
	s_nop 0
	global_load_lds_dwordx4 v[218:219], off
	v_lshl_add_u64 v[218:219], v[224:225], 0, s[22:23]
	s_mov_b32 m0, s78
	s_nop 0
	global_load_lds_dwordx4 v[218:219], off
	s_waitcnt vmcnt(8)
	s_waitcnt lgkmcnt(0)
	s_barrier
	v_mfma_i32_16x16x64_i8 v[54:57], v[130:133], v[186:189], v[54:57]
	v_mfma_i32_16x16x64_i8 v[18:21], v[162:165], v[186:189], v[18:21]
	v_mfma_i32_16x16x64_i8 v[50:53], v[130:133], v[194:197], v[50:53]
	v_mfma_i32_16x16x64_i8 v[22:25], v[162:165], v[194:197], v[22:25]
	v_mfma_i32_16x16x64_i8 v[62:65], v[130:133], v[202:205], v[62:65]
	v_mfma_i32_16x16x64_i8 v[30:33], v[162:165], v[202:205], v[30:33]
	v_mfma_i32_16x16x64_i8 v[58:61], v[130:133], v[210:213], v[58:61]
	v_mfma_i32_16x16x64_i8 v[26:29], v[162:165], v[210:213], v[26:29]
	v_mfma_i32_16x16x64_i8 v[54:57], v[134:137], v[190:193], v[54:57]
	v_mfma_i32_16x16x64_i8 v[18:21], v[166:169], v[190:193], v[18:21]
	v_mfma_i32_16x16x64_i8 v[50:53], v[134:137], v[198:201], v[50:53]
	v_mfma_i32_16x16x64_i8 v[22:25], v[166:169], v[198:201], v[22:25]
	v_mfma_i32_16x16x64_i8 v[62:65], v[134:137], v[206:209], v[62:65]
	v_mfma_i32_16x16x64_i8 v[30:33], v[166:169], v[206:209], v[30:33]
	v_mfma_i32_16x16x64_i8 v[58:61], v[134:137], v[214:217], v[58:61]
	v_mfma_i32_16x16x64_i8 v[26:29], v[166:169], v[214:217], v[26:29]
	v_mfma_i32_16x16x64_i8 v[46:49], v[170:173], v[186:189], v[46:49]
	v_mfma_i32_16x16x64_i8 v[14:17], v[178:181], v[186:189], v[14:17]
	v_mfma_i32_16x16x64_i8 v[42:45], v[170:173], v[194:197], v[42:45]
	v_mfma_i32_16x16x64_i8 v[10:13], v[178:181], v[194:197], v[10:13]
	v_mfma_i32_16x16x64_i8 v[38:41], v[170:173], v[202:205], v[38:41]
	v_mfma_i32_16x16x64_i8 v[6:9], v[178:181], v[202:205], v[6:9]
	v_mfma_i32_16x16x64_i8 v[34:37], v[170:173], v[210:213], v[34:37]
	v_mfma_i32_16x16x64_i8 v[2:5], v[178:181], v[210:213], v[2:5]
	v_mfma_i32_16x16x64_i8 v[46:49], v[174:177], v[190:193], v[46:49]
	v_mfma_i32_16x16x64_i8 v[14:17], v[182:185], v[190:193], v[14:17]
	v_mfma_i32_16x16x64_i8 v[42:45], v[174:177], v[198:201], v[42:45]
	v_mfma_i32_16x16x64_i8 v[10:13], v[182:185], v[198:201], v[10:13]
	v_mfma_i32_16x16x64_i8 v[38:41], v[174:177], v[206:209], v[38:41]
	v_mfma_i32_16x16x64_i8 v[6:9], v[182:185], v[206:209], v[6:9]
	v_mfma_i32_16x16x64_i8 v[34:37], v[174:177], v[214:217], v[34:37]
	v_mfma_i32_16x16x64_i8 v[2:5], v[182:185], v[214:217], v[2:5]
	s_barrier
	s_add_i32 s80, s80, 2
	s_add_u32 vcc_hi, vcc_hi, 0x100
	s_addc_u32 s79, s79, 0
	s_cmp_gt_u32 s80, 29
	s_mov_b64 s[4:5], s[6:7]
	s_cbranch_scc0 .LBB0_1367
	s_and_b64 vcc, exec, s[10:11]
	s_cbranch_vccz .LBB0_1370
	s_barrier

.LBB0_1554:
	ds_read_b128 v[114:117], v247
	ds_read_b128 v[118:121], v247 offset:1024
	ds_read_b128 v[126:129], v247 offset:2048
	ds_read_b128 v[134:137], v247 offset:3072
	ds_read_b128 v[138:141], v248
	ds_read_b128 v[142:145], v248 offset:1024
	ds_read_b128 v[154:157], v248 offset:2048
	ds_read_b128 v[158:161], v248 offset:3072
	s_add_u32 s4, s18, 0x100
	s_addc_u32 s5, s19, 0
	s_cmpk_eq_i32 s66, 0xdc
	s_cselect_b32 s29, s23, s5
	s_cselect_b32 s28, s22, s4
	s_cselect_b32 s27, s25, s65
	s_cselect_b32 s26, s24, s64
	v_lshl_add_u64 v[210:211], s[18:19], 0, v[202:203]
	s_add_i32 m0, s17, 0xc000
	ds_read_b128 v[162:165], v249
	ds_read_b128 v[166:169], v249 offset:1024
	ds_read_b128 v[170:173], v249 offset:2048
	ds_read_b128 v[174:177], v249 offset:3072
	ds_read_b128 v[178:181], v249 offset:4096
	ds_read_b128 v[182:185], v249 offset:5120
	ds_read_b128 v[186:189], v249 offset:6144
	ds_read_b128 v[190:193], v249 offset:7168
	global_load_lds_dwordx4 v[210:211], off
	v_lshl_add_u64 v[210:211], s[18:19], 0, v[204:205]
	s_add_i32 m0, s17, 0xe000
	s_nop 0
	global_load_lds_dwordx4 v[210:211], off
	s_waitcnt vmcnt(8)
	s_waitcnt lgkmcnt(0)
	s_barrier
	v_mfma_f32_16x16x32_bf16 v[150:153], v[114:117], v[162:165], v[150:153]
	v_mfma_f32_16x16x32_bf16 v[146:149], v[126:129], v[162:165], v[146:149]
	v_mfma_f32_16x16x32_bf16 v[110:113], v[114:117], v[170:173], v[110:113]
	v_mfma_f32_16x16x32_bf16 v[106:109], v[126:129], v[170:173], v[106:109]
	v_mfma_f32_16x16x32_bf16 v[94:97], v[114:117], v[178:181], v[94:97]
	v_mfma_f32_16x16x32_bf16 v[90:93], v[126:129], v[178:181], v[90:93]
	v_mfma_f32_16x16x32_bf16 v[78:81], v[114:117], v[186:189], v[78:81]
	v_mfma_f32_16x16x32_bf16 v[74:77], v[126:129], v[186:189], v[74:77]
	v_mfma_f32_16x16x32_bf16 v[150:153], v[118:121], v[166:169], v[150:153]
	v_mfma_f32_16x16x32_bf16 v[146:149], v[134:137], v[166:169], v[146:149]
	v_mfma_f32_16x16x32_bf16 v[110:113], v[118:121], v[174:177], v[110:113]
	v_mfma_f32_16x16x32_bf16 v[106:109], v[134:137], v[174:177], v[106:109]
	v_mfma_f32_16x16x32_bf16 v[94:97], v[118:121], v[182:185], v[94:97]
	v_mfma_f32_16x16x32_bf16 v[90:93], v[134:137], v[182:185], v[90:93]
	v_mfma_f32_16x16x32_bf16 v[78:81], v[118:121], v[190:193], v[78:81]
	v_mfma_f32_16x16x32_bf16 v[74:77], v[134:137], v[190:193], v[74:77]
	v_mfma_f32_16x16x32_bf16 v[130:133], v[138:141], v[162:165], v[130:133]
	v_mfma_f32_16x16x32_bf16 v[122:125], v[154:157], v[162:165], v[122:125]
	v_mfma_f32_16x16x32_bf16 v[102:105], v[138:141], v[170:173], v[102:105]
	v_mfma_f32_16x16x32_bf16 v[98:101], v[154:157], v[170:173], v[98:101]
	v_mfma_f32_16x16x32_bf16 v[86:89], v[138:141], v[178:181], v[86:89]
	v_mfma_f32_16x16x32_bf16 v[82:85], v[154:157], v[178:181], v[82:85]
	v_mfma_f32_16x16x32_bf16 v[70:73], v[138:141], v[186:189], v[70:73]
	v_mfma_f32_16x16x32_bf16 v[66:69], v[154:157], v[186:189], v[66:69]
	v_mfma_f32_16x16x32_bf16 v[130:133], v[142:145], v[166:169], v[130:133]
	v_mfma_f32_16x16x32_bf16 v[122:125], v[158:161], v[166:169], v[122:125]
	v_mfma_f32_16x16x32_bf16 v[102:105], v[142:145], v[174:177], v[102:105]
	v_mfma_f32_16x16x32_bf16 v[98:101], v[158:161], v[174:177], v[98:101]
	v_mfma_f32_16x16x32_bf16 v[86:89], v[142:145], v[182:185], v[86:89]
	v_mfma_f32_16x16x32_bf16 v[82:85], v[158:161], v[182:185], v[82:85]
	v_mfma_f32_16x16x32_bf16 v[70:73], v[142:145], v[190:193], v[70:73]
	v_mfma_f32_16x16x32_bf16 v[66:69], v[158:161], v[190:193], v[66:69]
	s_barrier
	s_add_i32 s18, s42, s16
	v_lshl_add_u64 v[210:211], s[26:27], 0, v[196:197]
	s_mov_b32 m0, s18
	ds_read_b128 v[162:165], v249 offset:16384
	ds_read_b128 v[166:169], v249 offset:17408
	ds_read_b128 v[170:173], v249 offset:18432
	ds_read_b128 v[174:177], v249 offset:19456
	ds_read_b128 v[178:181], v249 offset:20480
	ds_read_b128 v[182:185], v249 offset:21504
	ds_read_b128 v[186:189], v249 offset:22528
	ds_read_b128 v[190:193], v249 offset:23552
	global_load_lds_dwordx4 v[210:211], off
	s_add_i32 m0, s18, 0x2000
	s_add_u32 s18, s26, 0x380000
	v_lshl_add_u64 v[212:213], s[26:27], 0, v[200:201]
	s_addc_u32 s19, s27, 0
	s_add_i32 s67, s43, s16
	global_load_lds_dwordx4 v[212:213], off
	v_lshl_add_u64 v[214:215], s[18:19], 0, v[196:197]
	s_mov_b32 m0, s67
	v_lshl_add_u64 v[216:217], s[28:29], 0, v[198:199]
	global_load_lds_dwordx4 v[214:215], off
	v_lshl_add_u64 v[214:215], s[18:19], 0, v[200:201]
	s_add_i32 m0, s67, 0x2000
	s_nop 0
	global_load_lds_dwordx4 v[214:215], off
	v_lshl_add_u64 v[214:215], s[28:29], 0, v[194:195]
	s_mov_b32 m0, s17
	s_nop 0
	global_load_lds_dwordx4 v[214:215], off
	s_mov_b32 m0, s30
	s_nop 0
	global_load_lds_dwordx4 v[216:217], off
	s_waitcnt vmcnt(8)
	s_waitcnt lgkmcnt(0)
	s_barrier
	v_mfma_f32_16x16x32_bf16 v[62:65], v[114:117], v[162:165], v[62:65]
	v_mfma_f32_16x16x32_bf16 v[58:61], v[126:129], v[162:165], v[58:61]
	v_mfma_f32_16x16x32_bf16 v[46:49], v[114:117], v[170:173], v[46:49]
	v_mfma_f32_16x16x32_bf16 v[42:45], v[126:129], v[170:173], v[42:45]
	v_mfma_f32_16x16x32_bf16 v[30:33], v[114:117], v[178:181], v[30:33]
	v_mfma_f32_16x16x32_bf16 v[26:29], v[126:129], v[178:181], v[26:29]
	v_mfma_f32_16x16x32_bf16 v[14:17], v[114:117], v[186:189], v[14:17]
	v_mfma_f32_16x16x32_bf16 v[10:13], v[126:129], v[186:189], v[10:13]
	v_mfma_f32_16x16x32_bf16 v[62:65], v[118:121], v[166:169], v[62:65]
	v_mfma_f32_16x16x32_bf16 v[58:61], v[134:137], v[166:169], v[58:61]
	v_mfma_f32_16x16x32_bf16 v[46:49], v[118:121], v[174:177], v[46:49]
	v_mfma_f32_16x16x32_bf16 v[42:45], v[134:137], v[174:177], v[42:45]
	v_mfma_f32_16x16x32_bf16 v[30:33], v[118:121], v[182:185], v[30:33]
	v_mfma_f32_16x16x32_bf16 v[26:29], v[134:137], v[182:185], v[26:29]
	v_mfma_f32_16x16x32_bf16 v[14:17], v[118:121], v[190:193], v[14:17]
	v_mfma_f32_16x16x32_bf16 v[10:13], v[134:137], v[190:193], v[10:13]
	v_mfma_f32_16x16x32_bf16 v[54:57], v[138:141], v[162:165], v[54:57]
	v_mfma_f32_16x16x32_bf16 v[50:53], v[154:157], v[162:165], v[50:53]
	v_mfma_f32_16x16x32_bf16 v[38:41], v[138:141], v[170:173], v[38:41]
	v_mfma_f32_16x16x32_bf16 v[34:37], v[154:157], v[170:173], v[34:37]
	v_mfma_f32_16x16x32_bf16 v[22:25], v[138:141], v[178:181], v[22:25]
	v_mfma_f32_16x16x32_bf16 v[18:21], v[154:157], v[178:181], v[18:21]
	v_mfma_f32_16x16x32_bf16 v[6:9], v[138:141], v[186:189], v[6:9]
	v_mfma_f32_16x16x32_bf16 v[2:5], v[154:157], v[186:189], v[2:5]
	v_mfma_f32_16x16x32_bf16 v[54:57], v[142:145], v[166:169], v[54:57]
	v_mfma_f32_16x16x32_bf16 v[50:53], v[158:161], v[166:169], v[50:53]
	v_mfma_f32_16x16x32_bf16 v[38:41], v[142:145], v[174:177], v[38:41]
	v_mfma_f32_16x16x32_bf16 v[34:37], v[158:161], v[174:177], v[34:37]
	v_mfma_f32_16x16x32_bf16 v[22:25], v[142:145], v[182:185], v[22:25]
	v_mfma_f32_16x16x32_bf16 v[18:21], v[158:161], v[182:185], v[18:21]
	v_mfma_f32_16x16x32_bf16 v[6:9], v[142:145], v[190:193], v[6:9]
	v_mfma_f32_16x16x32_bf16 v[2:5], v[158:161], v[190:193], v[2:5]
	s_barrier
	s_add_i32 s67, 0, 0x18000
	s_add_i32 s68, 0, 0x1c000
	v_add_u32_e32 v134, s67, v244
	v_add_u32_e32 v158, s68, v244
	ds_read_b128 v[114:117], v134
	ds_read_b128 v[118:121], v134 offset:1024
	ds_read_b128 v[126:129], v134 offset:2048
	ds_read_b128 v[134:137], v134 offset:3072
	ds_read_b128 v[138:141], v158
	ds_read_b128 v[142:145], v158 offset:1024
	ds_read_b128 v[154:157], v158 offset:2048
	ds_read_b128 v[158:161], v158 offset:3072
	s_add_u32 s18, s28, 0x380000
	s_addc_u32 s19, s29, 0
	s_mov_b32 m0, s31
	v_lshl_add_u64 v[218:219], s[18:19], 0, v[194:195]
	ds_read_b128 v[162:165], v249 offset:32768
	ds_read_b128 v[166:169], v249 offset:33792
	ds_read_b128 v[170:173], v249 offset:34816
	ds_read_b128 v[174:177], v249 offset:35840
	ds_read_b128 v[178:181], v249 offset:36864
	ds_read_b128 v[182:185], v249 offset:37888
	ds_read_b128 v[186:189], v249 offset:38912
	ds_read_b128 v[190:193], v249 offset:39936
	global_load_lds_dwordx4 v[218:219], off
	v_lshl_add_u64 v[218:219], s[18:19], 0, v[198:199]
	s_mov_b32 m0, s34
	s_nop 0
	global_load_lds_dwordx4 v[218:219], off
	s_waitcnt vmcnt(8)
	s_waitcnt lgkmcnt(0)
	s_barrier
	v_mfma_f32_16x16x32_bf16 v[150:153], v[114:117], v[162:165], v[150:153]
	v_mfma_f32_16x16x32_bf16 v[146:149], v[126:129], v[162:165], v[146:149]
	v_mfma_f32_16x16x32_bf16 v[110:113], v[114:117], v[170:173], v[110:113]
	v_mfma_f32_16x16x32_bf16 v[106:109], v[126:129], v[170:173], v[106:109]
	v_mfma_f32_16x16x32_bf16 v[94:97], v[114:117], v[178:181], v[94:97]
	v_mfma_f32_16x16x32_bf16 v[90:93], v[126:129], v[178:181], v[90:93]
	v_mfma_f32_16x16x32_bf16 v[78:81], v[114:117], v[186:189], v[78:81]
	v_mfma_f32_16x16x32_bf16 v[74:77], v[126:129], v[186:189], v[74:77]
	v_mfma_f32_16x16x32_bf16 v[150:153], v[118:121], v[166:169], v[150:153]
	v_mfma_f32_16x16x32_bf16 v[146:149], v[134:137], v[166:169], v[146:149]
	v_mfma_f32_16x16x32_bf16 v[110:113], v[118:121], v[174:177], v[110:113]
	v_mfma_f32_16x16x32_bf16 v[106:109], v[134:137], v[174:177], v[106:109]
	v_mfma_f32_16x16x32_bf16 v[94:97], v[118:121], v[182:185], v[94:97]
	v_mfma_f32_16x16x32_bf16 v[90:93], v[134:137], v[182:185], v[90:93]
	v_mfma_f32_16x16x32_bf16 v[78:81], v[118:121], v[190:193], v[78:81]
	v_mfma_f32_16x16x32_bf16 v[74:77], v[134:137], v[190:193], v[74:77]
	v_mfma_f32_16x16x32_bf16 v[130:133], v[138:141], v[162:165], v[130:133]
	v_mfma_f32_16x16x32_bf16 v[122:125], v[154:157], v[162:165], v[122:125]
	v_mfma_f32_16x16x32_bf16 v[102:105], v[138:141], v[170:173], v[102:105]
	v_mfma_f32_16x16x32_bf16 v[98:101], v[154:157], v[170:173], v[98:101]
	v_mfma_f32_16x16x32_bf16 v[86:89], v[138:141], v[178:181], v[86:89]
	v_mfma_f32_16x16x32_bf16 v[82:85], v[154:157], v[178:181], v[82:85]
	v_mfma_f32_16x16x32_bf16 v[70:73], v[138:141], v[186:189], v[70:73]
	v_mfma_f32_16x16x32_bf16 v[66:69], v[154:157], v[186:189], v[66:69]
	v_mfma_f32_16x16x32_bf16 v[130:133], v[142:145], v[166:169], v[130:133]
	v_mfma_f32_16x16x32_bf16 v[122:125], v[158:161], v[166:169], v[122:125]
	v_mfma_f32_16x16x32_bf16 v[102:105], v[142:145], v[174:177], v[102:105]
	v_mfma_f32_16x16x32_bf16 v[98:101], v[158:161], v[174:177], v[98:101]
	v_mfma_f32_16x16x32_bf16 v[86:89], v[142:145], v[182:185], v[86:89]
	v_mfma_f32_16x16x32_bf16 v[82:85], v[158:161], v[182:185], v[82:85]
	v_mfma_f32_16x16x32_bf16 v[70:73], v[142:145], v[190:193], v[70:73]
	v_mfma_f32_16x16x32_bf16 v[66:69], v[158:161], v[190:193], v[66:69]
	s_barrier
	s_add_i32 s18, s67, s16
	v_lshl_add_u64 v[210:211], v[210:211], 0, s[12:13]
	s_mov_b32 m0, s18
	ds_read_b128 v[162:165], v249 offset:49152
	ds_read_b128 v[166:169], v249 offset:50176
	ds_read_b128 v[170:173], v249 offset:51200
	ds_read_b128 v[174:177], v249 offset:52224
	ds_read_b128 v[178:181], v249 offset:53248
	ds_read_b128 v[182:185], v249 offset:54272
	ds_read_b128 v[186:189], v249 offset:55296
	ds_read_b128 v[190:193], v249 offset:56320
	global_load_lds_dwordx4 v[210:211], off
	s_add_i32 m0, s18, 0x2000
	s_add_u32 s18, s26, 0x380080
	v_lshl_add_u64 v[210:211], v[212:213], 0, s[12:13]
	s_addc_u32 s19, s27, 0
	s_add_i32 s26, s68, s16
	global_load_lds_dwordx4 v[210:211], off
	v_lshl_add_u64 v[210:211], s[18:19], 0, v[196:197]
	s_mov_b32 m0, s26
	s_nop 0
	global_load_lds_dwordx4 v[210:211], off
	v_lshl_add_u64 v[210:211], s[18:19], 0, v[200:201]
	s_add_i32 m0, s26, 0x2000
	s_nop 0
	global_load_lds_dwordx4 v[210:211], off
	v_lshl_add_u64 v[210:211], v[214:215], 0, s[12:13]
	s_mov_b32 m0, s38
	s_nop 0
	global_load_lds_dwordx4 v[210:211], off
	v_lshl_add_u64 v[210:211], v[216:217], 0, s[12:13]
	s_mov_b32 m0, s39
	s_nop 0
	global_load_lds_dwordx4 v[210:211], off
	s_waitcnt vmcnt(8)
	s_waitcnt lgkmcnt(0)
	s_barrier
	v_mfma_f32_16x16x32_bf16 v[62:65], v[114:117], v[162:165], v[62:65]
	v_mfma_f32_16x16x32_bf16 v[58:61], v[126:129], v[162:165], v[58:61]
	v_mfma_f32_16x16x32_bf16 v[46:49], v[114:117], v[170:173], v[46:49]
	v_mfma_f32_16x16x32_bf16 v[42:45], v[126:129], v[170:173], v[42:45]
	v_mfma_f32_16x16x32_bf16 v[30:33], v[114:117], v[178:181], v[30:33]
	v_mfma_f32_16x16x32_bf16 v[26:29], v[126:129], v[178:181], v[26:29]
	v_mfma_f32_16x16x32_bf16 v[14:17], v[114:117], v[186:189], v[14:17]
	v_mfma_f32_16x16x32_bf16 v[10:13], v[126:129], v[186:189], v[10:13]
	v_mfma_f32_16x16x32_bf16 v[62:65], v[118:121], v[166:169], v[62:65]
	v_mfma_f32_16x16x32_bf16 v[58:61], v[134:137], v[166:169], v[58:61]
	v_mfma_f32_16x16x32_bf16 v[46:49], v[118:121], v[174:177], v[46:49]
	v_mfma_f32_16x16x32_bf16 v[42:45], v[134:137], v[174:177], v[42:45]
	v_mfma_f32_16x16x32_bf16 v[30:33], v[118:121], v[182:185], v[30:33]
	v_mfma_f32_16x16x32_bf16 v[26:29], v[134:137], v[182:185], v[26:29]
	v_mfma_f32_16x16x32_bf16 v[14:17], v[118:121], v[190:193], v[14:17]
	v_mfma_f32_16x16x32_bf16 v[10:13], v[134:137], v[190:193], v[10:13]
	v_mfma_f32_16x16x32_bf16 v[54:57], v[138:141], v[162:165], v[54:57]
	v_mfma_f32_16x16x32_bf16 v[50:53], v[154:157], v[162:165], v[50:53]
	v_mfma_f32_16x16x32_bf16 v[38:41], v[138:141], v[170:173], v[38:41]
	v_mfma_f32_16x16x32_bf16 v[34:37], v[154:157], v[170:173], v[34:37]
	v_mfma_f32_16x16x32_bf16 v[22:25], v[138:141], v[178:181], v[22:25]
	v_mfma_f32_16x16x32_bf16 v[18:21], v[154:157], v[178:181], v[18:21]
	v_mfma_f32_16x16x32_bf16 v[6:9], v[138:141], v[186:189], v[6:9]
	v_mfma_f32_16x16x32_bf16 v[2:5], v[154:157], v[186:189], v[2:5]
	v_mfma_f32_16x16x32_bf16 v[54:57], v[142:145], v[166:169], v[54:57]
	v_mfma_f32_16x16x32_bf16 v[50:53], v[158:161], v[166:169], v[50:53]
	v_mfma_f32_16x16x32_bf16 v[38:41], v[142:145], v[174:177], v[38:41]
	v_mfma_f32_16x16x32_bf16 v[34:37], v[158:161], v[174:177], v[34:37]
	v_mfma_f32_16x16x32_bf16 v[22:25], v[142:145], v[182:185], v[22:25]
	v_mfma_f32_16x16x32_bf16 v[18:21], v[158:161], v[182:185], v[18:21]
	v_mfma_f32_16x16x32_bf16 v[6:9], v[142:145], v[190:193], v[6:9]
	v_mfma_f32_16x16x32_bf16 v[2:5], v[158:161], v[190:193], v[2:5]
	s_barrier
	s_add_i32 s66, s66, 2
	s_add_u32 s64, s64, 0x100
	s_addc_u32 s65, s65, 0
	s_cmpk_gt_u32 s66, 0xdd
	s_mov_b64 s[18:19], s[4:5]
	s_cbranch_scc0 .LBB0_1554
	s_and_b64 vcc, exec, s[14:15]
	s_cbranch_vccz .LBB0_1557
	s_barrier

.LBB0_1647:
	ds_read_b128 v[30:33], v200
	ds_read_b128 v[38:41], v200 offset:1024
	ds_read_b128 v[42:45], v200 offset:2048
	ds_read_b128 v[50:53], v200 offset:3072
	ds_read_b128 v[164:167], v201
	ds_read_b128 v[168:171], v201 offset:1024
	ds_read_b128 v[172:175], v201 offset:2048
	ds_read_b128 v[176:179], v201 offset:3072
	s_add_u32 s18, s10, 0xfff00080
	s_addc_u32 s19, s11, -1
	s_cmp_eq_u32 s61, 60
	s_cselect_b32 s69, s0, s19
	s_cselect_b32 s68, s1, s18
	s_cselect_b32 s19, s7, s17
	s_cselect_b32 s18, s9, s16
	v_lshl_add_u64 v[222:223], s[10:11], 0, v[156:157]
	s_add_i32 m0, s39, 0xc000
	ds_read_b128 v[180:183], v202
	ds_read_b128 v[184:187], v202 offset:1024
	ds_read_b128 v[188:191], v202 offset:2048
	ds_read_b128 v[192:195], v202 offset:3072
	ds_read_b128 v[206:209], v202 offset:4096
	ds_read_b128 v[210:213], v202 offset:5120
	ds_read_b128 v[214:217], v202 offset:6144
	ds_read_b128 v[218:221], v202 offset:7168
	global_load_lds_dwordx4 v[222:223], off
	v_lshl_add_u64 v[222:223], s[10:11], 0, v[158:159]
	s_add_i32 m0, s39, 0xe000
	s_nop 0
	global_load_lds_dwordx4 v[222:223], off
	s_waitcnt vmcnt(8)
	s_waitcnt lgkmcnt(0)
	s_barrier
	v_mfma_f32_16x16x32_bf16 v[138:141], v[30:33], v[180:183], v[138:141]
	v_mfma_f32_16x16x32_bf16 v[142:145], v[42:45], v[180:183], v[142:145]
	v_mfma_f32_16x16x32_bf16 v[122:125], v[30:33], v[188:191], v[122:125]
	v_mfma_f32_16x16x32_bf16 v[126:129], v[42:45], v[188:191], v[126:129]
	v_mfma_f32_16x16x32_bf16 v[106:109], v[30:33], v[206:209], v[106:109]
	v_mfma_f32_16x16x32_bf16 v[110:113], v[42:45], v[206:209], v[110:113]
	v_mfma_f32_16x16x32_bf16 v[90:93], v[30:33], v[214:217], v[90:93]
	v_mfma_f32_16x16x32_bf16 v[94:97], v[42:45], v[214:217], v[94:97]
	v_mfma_f32_16x16x32_bf16 v[138:141], v[38:41], v[184:187], v[138:141]
	v_mfma_f32_16x16x32_bf16 v[142:145], v[50:53], v[184:187], v[142:145]
	v_mfma_f32_16x16x32_bf16 v[122:125], v[38:41], v[192:195], v[122:125]
	v_mfma_f32_16x16x32_bf16 v[126:129], v[50:53], v[192:195], v[126:129]
	v_mfma_f32_16x16x32_bf16 v[106:109], v[38:41], v[210:213], v[106:109]
	v_mfma_f32_16x16x32_bf16 v[110:113], v[50:53], v[210:213], v[110:113]
	v_mfma_f32_16x16x32_bf16 v[90:93], v[38:41], v[218:221], v[90:93]
	v_mfma_f32_16x16x32_bf16 v[94:97], v[50:53], v[218:221], v[94:97]
	v_mfma_f32_16x16x32_bf16 v[130:133], v[164:167], v[180:183], v[130:133]
	v_mfma_f32_16x16x32_bf16 v[134:137], v[172:175], v[180:183], v[134:137]
	v_mfma_f32_16x16x32_bf16 v[114:117], v[164:167], v[188:191], v[114:117]
	v_mfma_f32_16x16x32_bf16 v[118:121], v[172:175], v[188:191], v[118:121]
	v_mfma_f32_16x16x32_bf16 v[98:101], v[164:167], v[206:209], v[98:101]
	v_mfma_f32_16x16x32_bf16 v[102:105], v[172:175], v[206:209], v[102:105]
	v_mfma_f32_16x16x32_bf16 v[82:85], v[164:167], v[214:217], v[82:85]
	v_mfma_f32_16x16x32_bf16 v[86:89], v[172:175], v[214:217], v[86:89]
	v_mfma_f32_16x16x32_bf16 v[130:133], v[168:171], v[184:187], v[130:133]
	v_mfma_f32_16x16x32_bf16 v[134:137], v[176:179], v[184:187], v[134:137]
	v_mfma_f32_16x16x32_bf16 v[114:117], v[168:171], v[192:195], v[114:117]
	v_mfma_f32_16x16x32_bf16 v[118:121], v[176:179], v[192:195], v[118:121]
	v_mfma_f32_16x16x32_bf16 v[98:101], v[168:171], v[210:213], v[98:101]
	v_mfma_f32_16x16x32_bf16 v[102:105], v[176:179], v[210:213], v[102:105]
	v_mfma_f32_16x16x32_bf16 v[82:85], v[168:171], v[218:221], v[82:85]
	v_mfma_f32_16x16x32_bf16 v[86:89], v[176:179], v[218:221], v[86:89]
	s_barrier
	s_add_i32 s63, s77, s37
	v_lshl_add_u64 v[222:223], s[18:19], 0, v[148:149]
	s_mov_b32 m0, s63
	ds_read_b128 v[180:183], v202 offset:16384
	ds_read_b128 v[184:187], v202 offset:17408
	ds_read_b128 v[188:191], v202 offset:18432
	ds_read_b128 v[192:195], v202 offset:19456
	ds_read_b128 v[206:209], v202 offset:20480
	ds_read_b128 v[210:213], v202 offset:21504
	ds_read_b128 v[214:217], v202 offset:22528
	ds_read_b128 v[218:221], v202 offset:23552
	global_load_lds_dwordx4 v[222:223], off
	s_add_i32 m0, s63, 0x2000
	s_add_u32 s82, s18, 0x100000
	v_lshl_add_u64 v[224:225], s[18:19], 0, v[152:153]
	s_addc_u32 s83, s19, 0
	s_add_i32 s63, s78, s37
	global_load_lds_dwordx4 v[224:225], off
	v_lshl_add_u64 v[226:227], s[82:83], 0, v[148:149]
	s_mov_b32 m0, s63
	v_lshl_add_u64 v[228:229], s[68:69], 0, v[150:151]
	global_load_lds_dwordx4 v[226:227], off
	v_lshl_add_u64 v[226:227], s[82:83], 0, v[152:153]
	s_add_i32 m0, s63, 0x2000
	s_nop 0
	global_load_lds_dwordx4 v[226:227], off
	v_lshl_add_u64 v[226:227], s[68:69], 0, v[146:147]
	s_mov_b32 m0, s39
	s_nop 0
	global_load_lds_dwordx4 v[226:227], off
	s_mov_b32 m0, s41
	s_nop 0
	global_load_lds_dwordx4 v[228:229], off
	s_waitcnt vmcnt(8)
	s_waitcnt lgkmcnt(0)
	s_barrier
	v_mfma_f32_16x16x32_bf16 v[74:77], v[30:33], v[180:183], v[74:77]
	v_mfma_f32_16x16x32_bf16 v[78:81], v[42:45], v[180:183], v[78:81]
	v_mfma_f32_16x16x32_bf16 v[58:61], v[30:33], v[188:191], v[58:61]
	v_mfma_f32_16x16x32_bf16 v[62:65], v[42:45], v[188:191], v[62:65]
	v_mfma_f32_16x16x32_bf16 v[26:29], v[30:33], v[206:209], v[26:29]
	v_mfma_f32_16x16x32_bf16 v[34:37], v[42:45], v[206:209], v[34:37]
	v_mfma_f32_16x16x32_bf16 v[10:13], v[30:33], v[214:217], v[10:13]
	v_mfma_f32_16x16x32_bf16 v[14:17], v[42:45], v[214:217], v[14:17]
	v_mfma_f32_16x16x32_bf16 v[74:77], v[38:41], v[184:187], v[74:77]
	v_mfma_f32_16x16x32_bf16 v[78:81], v[50:53], v[184:187], v[78:81]
	v_mfma_f32_16x16x32_bf16 v[58:61], v[38:41], v[192:195], v[58:61]
	v_mfma_f32_16x16x32_bf16 v[62:65], v[50:53], v[192:195], v[62:65]
	v_mfma_f32_16x16x32_bf16 v[26:29], v[38:41], v[210:213], v[26:29]
	v_mfma_f32_16x16x32_bf16 v[34:37], v[50:53], v[210:213], v[34:37]
	v_mfma_f32_16x16x32_bf16 v[10:13], v[38:41], v[218:221], v[10:13]
	v_mfma_f32_16x16x32_bf16 v[14:17], v[50:53], v[218:221], v[14:17]
	v_mfma_f32_16x16x32_bf16 v[18:21], v[164:167], v[206:209], v[18:21]
	v_mfma_f32_16x16x32_bf16 v[22:25], v[172:175], v[206:209], v[22:25]
	v_mfma_f32_16x16x32_bf16 v[2:5], v[164:167], v[214:217], v[2:5]
	v_mfma_f32_16x16x32_bf16 v[6:9], v[172:175], v[214:217], v[6:9]
	v_mfma_f32_16x16x32_bf16 v[30:33], v[164:167], v[180:183], v[66:69]
	v_mfma_f32_16x16x32_bf16 v[38:41], v[172:175], v[180:183], v[70:73]
	v_mfma_f32_16x16x32_bf16 v[42:45], v[164:167], v[188:191], v[46:49]
	v_mfma_f32_16x16x32_bf16 v[46:49], v[172:175], v[188:191], v[54:57]
	v_mfma_f32_16x16x32_bf16 v[18:21], v[168:171], v[210:213], v[18:21]
	v_mfma_f32_16x16x32_bf16 v[22:25], v[176:179], v[210:213], v[22:25]
	v_mfma_f32_16x16x32_bf16 v[2:5], v[168:171], v[218:221], v[2:5]
	v_mfma_f32_16x16x32_bf16 v[6:9], v[176:179], v[218:221], v[6:9]
	v_mfma_f32_16x16x32_bf16 v[30:33], v[168:171], v[184:187], v[30:33]
	v_mfma_f32_16x16x32_bf16 v[38:41], v[176:179], v[184:187], v[38:41]
	v_mfma_f32_16x16x32_bf16 v[42:45], v[168:171], v[192:195], v[42:45]
	v_mfma_f32_16x16x32_bf16 v[50:53], v[176:179], v[192:195], v[46:49]
	s_barrier
	s_add_i32 s63, 0, 0x18000
	s_add_i32 s82, 0, 0x1c000
	v_add_u32_e32 v70, s63, v196
	v_add_u32_e32 v155, s82, v196
	ds_read_b128 v[46:49], v70
	ds_read_b128 v[54:57], v70 offset:1024
	ds_read_b128 v[66:69], v70 offset:2048
	ds_read_b128 v[70:73], v70 offset:3072
	ds_read_b128 v[164:167], v155
	ds_read_b128 v[168:171], v155 offset:1024
	ds_read_b128 v[172:175], v155 offset:2048
	ds_read_b128 v[176:179], v155 offset:3072
	s_add_u32 s68, s68, 0x100000
	s_addc_u32 s69, s69, 0
	s_mov_b32 m0, s43
	v_lshl_add_u64 v[230:231], s[68:69], 0, v[146:147]
	ds_read_b128 v[180:183], v202 offset:32768
	ds_read_b128 v[184:187], v202 offset:33792
	ds_read_b128 v[188:191], v202 offset:34816
	ds_read_b128 v[192:195], v202 offset:35840
	ds_read_b128 v[206:209], v202 offset:36864
	ds_read_b128 v[210:213], v202 offset:37888
	ds_read_b128 v[214:217], v202 offset:38912
	ds_read_b128 v[218:221], v202 offset:39936
	global_load_lds_dwordx4 v[230:231], off
	v_lshl_add_u64 v[230:231], s[68:69], 0, v[150:151]
	s_mov_b32 m0, s57
	s_nop 0
	global_load_lds_dwordx4 v[230:231], off
	s_waitcnt vmcnt(8)
	s_waitcnt lgkmcnt(0)
	s_barrier
	v_mfma_f32_16x16x32_bf16 v[138:141], v[46:49], v[180:183], v[138:141]
	v_mfma_f32_16x16x32_bf16 v[142:145], v[66:69], v[180:183], v[142:145]
	v_mfma_f32_16x16x32_bf16 v[122:125], v[46:49], v[188:191], v[122:125]
	v_mfma_f32_16x16x32_bf16 v[126:129], v[66:69], v[188:191], v[126:129]
	v_mfma_f32_16x16x32_bf16 v[106:109], v[46:49], v[206:209], v[106:109]
	v_mfma_f32_16x16x32_bf16 v[110:113], v[66:69], v[206:209], v[110:113]
	v_mfma_f32_16x16x32_bf16 v[90:93], v[46:49], v[214:217], v[90:93]
	v_mfma_f32_16x16x32_bf16 v[94:97], v[66:69], v[214:217], v[94:97]
	v_mfma_f32_16x16x32_bf16 v[138:141], v[54:57], v[184:187], v[138:141]
	v_mfma_f32_16x16x32_bf16 v[142:145], v[70:73], v[184:187], v[142:145]
	v_mfma_f32_16x16x32_bf16 v[122:125], v[54:57], v[192:195], v[122:125]
	v_mfma_f32_16x16x32_bf16 v[126:129], v[70:73], v[192:195], v[126:129]
	v_mfma_f32_16x16x32_bf16 v[106:109], v[54:57], v[210:213], v[106:109]
	v_mfma_f32_16x16x32_bf16 v[110:113], v[70:73], v[210:213], v[110:113]
	v_mfma_f32_16x16x32_bf16 v[90:93], v[54:57], v[218:221], v[90:93]
	v_mfma_f32_16x16x32_bf16 v[94:97], v[70:73], v[218:221], v[94:97]
	v_mfma_f32_16x16x32_bf16 v[130:133], v[164:167], v[180:183], v[130:133]
	v_mfma_f32_16x16x32_bf16 v[134:137], v[172:175], v[180:183], v[134:137]
	v_mfma_f32_16x16x32_bf16 v[114:117], v[164:167], v[188:191], v[114:117]
	v_mfma_f32_16x16x32_bf16 v[118:121], v[172:175], v[188:191], v[118:121]
	v_mfma_f32_16x16x32_bf16 v[98:101], v[164:167], v[206:209], v[98:101]
	v_mfma_f32_16x16x32_bf16 v[102:105], v[172:175], v[206:209], v[102:105]
	v_mfma_f32_16x16x32_bf16 v[82:85], v[164:167], v[214:217], v[82:85]
	v_mfma_f32_16x16x32_bf16 v[86:89], v[172:175], v[214:217], v[86:89]
	v_mfma_f32_16x16x32_bf16 v[130:133], v[168:171], v[184:187], v[130:133]
	v_mfma_f32_16x16x32_bf16 v[134:137], v[176:179], v[184:187], v[134:137]
	v_mfma_f32_16x16x32_bf16 v[114:117], v[168:171], v[192:195], v[114:117]
	v_mfma_f32_16x16x32_bf16 v[118:121], v[176:179], v[192:195], v[118:121]
	v_mfma_f32_16x16x32_bf16 v[98:101], v[168:171], v[210:213], v[98:101]
	v_mfma_f32_16x16x32_bf16 v[102:105], v[176:179], v[210:213], v[102:105]
	v_mfma_f32_16x16x32_bf16 v[82:85], v[168:171], v[218:221], v[82:85]
	v_mfma_f32_16x16x32_bf16 v[86:89], v[176:179], v[218:221], v[86:89]
	s_barrier
	s_add_i32 s63, s63, s37
	v_lshl_add_u64 v[222:223], v[222:223], 0, s[26:27]
	s_mov_b32 m0, s63
	ds_read_b128 v[180:183], v202 offset:49152
	ds_read_b128 v[184:187], v202 offset:50176
	ds_read_b128 v[188:191], v202 offset:51200
	ds_read_b128 v[192:195], v202 offset:52224
	ds_read_b128 v[206:209], v202 offset:53248
	ds_read_b128 v[210:213], v202 offset:54272
	ds_read_b128 v[214:217], v202 offset:55296
	ds_read_b128 v[218:221], v202 offset:56320
	global_load_lds_dwordx4 v[222:223], off
	s_add_i32 m0, s63, 0x2000
	s_add_u32 s18, s18, 0x100080
	v_lshl_add_u64 v[222:223], v[224:225], 0, s[26:27]
	s_addc_u32 s19, s19, 0
	s_add_i32 s63, s82, s37
	global_load_lds_dwordx4 v[222:223], off
	v_lshl_add_u64 v[222:223], s[18:19], 0, v[148:149]
	s_mov_b32 m0, s63
	s_nop 0
	global_load_lds_dwordx4 v[222:223], off
	v_lshl_add_u64 v[222:223], s[18:19], 0, v[152:153]
	s_add_i32 m0, s63, 0x2000
	s_nop 0
	global_load_lds_dwordx4 v[222:223], off
	v_lshl_add_u64 v[222:223], v[226:227], 0, s[26:27]
	s_mov_b32 m0, s71
	s_nop 0
	global_load_lds_dwordx4 v[222:223], off
	v_lshl_add_u64 v[222:223], v[228:229], 0, s[26:27]
	s_mov_b32 m0, s72
	s_nop 0
	global_load_lds_dwordx4 v[222:223], off
	s_waitcnt vmcnt(8)
	s_waitcnt lgkmcnt(0)
	s_barrier
	v_mfma_f32_16x16x32_bf16 v[74:77], v[46:49], v[180:183], v[74:77]
	v_mfma_f32_16x16x32_bf16 v[78:81], v[66:69], v[180:183], v[78:81]
	v_mfma_f32_16x16x32_bf16 v[58:61], v[46:49], v[188:191], v[58:61]
	v_mfma_f32_16x16x32_bf16 v[62:65], v[66:69], v[188:191], v[62:65]
	v_mfma_f32_16x16x32_bf16 v[26:29], v[46:49], v[206:209], v[26:29]
	v_mfma_f32_16x16x32_bf16 v[34:37], v[66:69], v[206:209], v[34:37]
	v_mfma_f32_16x16x32_bf16 v[10:13], v[46:49], v[214:217], v[10:13]
	v_mfma_f32_16x16x32_bf16 v[14:17], v[66:69], v[214:217], v[14:17]
	v_mfma_f32_16x16x32_bf16 v[74:77], v[54:57], v[184:187], v[74:77]
	v_mfma_f32_16x16x32_bf16 v[78:81], v[70:73], v[184:187], v[78:81]
	v_mfma_f32_16x16x32_bf16 v[58:61], v[54:57], v[192:195], v[58:61]
	v_mfma_f32_16x16x32_bf16 v[62:65], v[70:73], v[192:195], v[62:65]
	v_mfma_f32_16x16x32_bf16 v[26:29], v[54:57], v[210:213], v[26:29]
	v_mfma_f32_16x16x32_bf16 v[34:37], v[70:73], v[210:213], v[34:37]
	v_mfma_f32_16x16x32_bf16 v[10:13], v[54:57], v[218:221], v[10:13]
	v_mfma_f32_16x16x32_bf16 v[14:17], v[70:73], v[218:221], v[14:17]
	v_mfma_f32_16x16x32_bf16 v[30:33], v[164:167], v[180:183], v[30:33]
	v_mfma_f32_16x16x32_bf16 v[66:69], v[168:171], v[184:187], v[30:33]
	v_mfma_f32_16x16x32_bf16 v[30:33], v[172:175], v[180:183], v[38:41]
	v_mfma_f32_16x16x32_bf16 v[70:73], v[176:179], v[184:187], v[30:33]
	v_mfma_f32_16x16x32_bf16 v[30:33], v[164:167], v[188:191], v[42:45]
	v_mfma_f32_16x16x32_bf16 v[46:49], v[168:171], v[192:195], v[30:33]
	v_mfma_f32_16x16x32_bf16 v[30:33], v[172:175], v[188:191], v[50:53]
	v_mfma_f32_16x16x32_bf16 v[18:21], v[164:167], v[206:209], v[18:21]
	v_mfma_f32_16x16x32_bf16 v[22:25], v[172:175], v[206:209], v[22:25]
	v_mfma_f32_16x16x32_bf16 v[2:5], v[164:167], v[214:217], v[2:5]
	v_mfma_f32_16x16x32_bf16 v[6:9], v[172:175], v[214:217], v[6:9]
	v_mfma_f32_16x16x32_bf16 v[54:57], v[176:179], v[192:195], v[30:33]
	v_mfma_f32_16x16x32_bf16 v[18:21], v[168:171], v[210:213], v[18:21]
	v_mfma_f32_16x16x32_bf16 v[22:25], v[176:179], v[210:213], v[22:25]
	v_mfma_f32_16x16x32_bf16 v[2:5], v[168:171], v[218:221], v[2:5]
	v_mfma_f32_16x16x32_bf16 v[6:9], v[176:179], v[218:221], v[6:9]
	s_barrier
	s_add_i32 s61, s61, 2
	s_add_u32 s10, s10, 0x100
	s_addc_u32 s11, s11, 0
	s_add_u32 s16, s16, 0x100
	s_addc_u32 s17, s17, 0
	s_cmp_gt_u32 s61, 61
	s_cbranch_scc0 .LBB0_1647
	s_and_b64 vcc, exec, s[28:29]
	s_cbranch_vccz .LBB0_1650
	s_barrier

.LBB0_1921:
	ds_read_b128 v[130:133], v212
	ds_read_b128 v[134:137], v212 offset:1024
	ds_read_b128 v[138:141], v212 offset:2048
	ds_read_b128 v[142:145], v212 offset:3072
	ds_read_b128 v[146:149], v213
	ds_read_b128 v[150:153], v213 offset:1024
	ds_read_b128 v[154:157], v213 offset:2048
	ds_read_b128 v[158:161], v213 offset:3072
	s_add_u32 s40, s38, 0xfff00080
	s_addc_u32 s41, s39, -1
	s_cmp_eq_u32 s73, 60
	s_cselect_b32 s43, s31, s41
	s_cselect_b32 s42, s69, s40
	s_cselect_b32 s41, s29, s72
	s_cselect_b32 s40, s70, s71
	v_lshl_add_u64 v[216:217], s[38:39], 0, v[178:179]
	s_add_i32 m0, s19, 0xc000
	ds_read_b128 v[162:165], v214
	ds_read_b128 v[166:169], v214 offset:1024
	ds_read_b128 v[186:189], v214 offset:2048
	ds_read_b128 v[190:193], v214 offset:3072
	ds_read_b128 v[194:197], v214 offset:4096
	ds_read_b128 v[198:201], v214 offset:5120
	ds_read_b128 v[202:205], v214 offset:6144
	ds_read_b128 v[206:209], v214 offset:7168
	global_load_lds_dwordx4 v[216:217], off
	v_lshl_add_u64 v[216:217], s[38:39], 0, v[180:181]
	s_add_i32 m0, s19, 0xe000
	s_nop 0
	global_load_lds_dwordx4 v[216:217], off
	s_waitcnt vmcnt(8)
	s_waitcnt lgkmcnt(0)
	s_barrier
	v_mfma_f32_16x16x32_bf16 v[126:129], v[130:133], v[162:165], v[126:129]
	v_mfma_f32_16x16x32_bf16 v[122:125], v[138:141], v[162:165], v[122:125]
	v_mfma_f32_16x16x32_bf16 v[110:113], v[130:133], v[186:189], v[110:113]
	v_mfma_f32_16x16x32_bf16 v[106:109], v[138:141], v[186:189], v[106:109]
	v_mfma_f32_16x16x32_bf16 v[94:97], v[130:133], v[194:197], v[94:97]
	v_mfma_f32_16x16x32_bf16 v[90:93], v[138:141], v[194:197], v[90:93]
	v_mfma_f32_16x16x32_bf16 v[78:81], v[130:133], v[202:205], v[78:81]
	v_mfma_f32_16x16x32_bf16 v[74:77], v[138:141], v[202:205], v[74:77]
	v_mfma_f32_16x16x32_bf16 v[126:129], v[134:137], v[166:169], v[126:129]
	v_mfma_f32_16x16x32_bf16 v[122:125], v[142:145], v[166:169], v[122:125]
	v_mfma_f32_16x16x32_bf16 v[110:113], v[134:137], v[190:193], v[110:113]
	v_mfma_f32_16x16x32_bf16 v[106:109], v[142:145], v[190:193], v[106:109]
	v_mfma_f32_16x16x32_bf16 v[94:97], v[134:137], v[198:201], v[94:97]
	v_mfma_f32_16x16x32_bf16 v[90:93], v[142:145], v[198:201], v[90:93]
	v_mfma_f32_16x16x32_bf16 v[78:81], v[134:137], v[206:209], v[78:81]
	v_mfma_f32_16x16x32_bf16 v[74:77], v[142:145], v[206:209], v[74:77]
	v_mfma_f32_16x16x32_bf16 v[118:121], v[146:149], v[162:165], v[118:121]
	v_mfma_f32_16x16x32_bf16 v[114:117], v[154:157], v[162:165], v[114:117]
	v_mfma_f32_16x16x32_bf16 v[102:105], v[146:149], v[186:189], v[102:105]
	v_mfma_f32_16x16x32_bf16 v[98:101], v[154:157], v[186:189], v[98:101]
	v_mfma_f32_16x16x32_bf16 v[86:89], v[146:149], v[194:197], v[86:89]
	v_mfma_f32_16x16x32_bf16 v[82:85], v[154:157], v[194:197], v[82:85]
	v_mfma_f32_16x16x32_bf16 v[70:73], v[146:149], v[202:205], v[70:73]
	v_mfma_f32_16x16x32_bf16 v[66:69], v[154:157], v[202:205], v[66:69]
	v_mfma_f32_16x16x32_bf16 v[118:121], v[150:153], v[166:169], v[118:121]
	v_mfma_f32_16x16x32_bf16 v[114:117], v[158:161], v[166:169], v[114:117]
	v_mfma_f32_16x16x32_bf16 v[102:105], v[150:153], v[190:193], v[102:105]
	v_mfma_f32_16x16x32_bf16 v[98:101], v[158:161], v[190:193], v[98:101]
	v_mfma_f32_16x16x32_bf16 v[86:89], v[150:153], v[198:201], v[86:89]
	v_mfma_f32_16x16x32_bf16 v[82:85], v[158:161], v[198:201], v[82:85]
	v_mfma_f32_16x16x32_bf16 v[70:73], v[150:153], v[206:209], v[70:73]
	v_mfma_f32_16x16x32_bf16 v[66:69], v[158:161], v[206:209], v[66:69]
	s_barrier
	s_add_i32 s76, s57, s17
	v_lshl_add_u64 v[216:217], s[40:41], 0, v[172:173]
	s_mov_b32 m0, s76
	ds_read_b128 v[162:165], v214 offset:16384
	ds_read_b128 v[166:169], v214 offset:17408
	ds_read_b128 v[186:189], v214 offset:18432
	ds_read_b128 v[190:193], v214 offset:19456
	ds_read_b128 v[194:197], v214 offset:20480
	ds_read_b128 v[198:201], v214 offset:21504
	ds_read_b128 v[202:205], v214 offset:22528
	ds_read_b128 v[206:209], v214 offset:23552
	global_load_lds_dwordx4 v[216:217], off
	s_add_i32 m0, s76, 0x2000
	s_add_u32 s76, s40, 0x100000
	v_lshl_add_u64 v[218:219], s[40:41], 0, v[176:177]
	s_addc_u32 s77, s41, 0
	s_add_i32 s78, s60, s17
	global_load_lds_dwordx4 v[218:219], off
	v_lshl_add_u64 v[220:221], s[76:77], 0, v[172:173]
	s_mov_b32 m0, s78
	v_lshl_add_u64 v[222:223], s[42:43], 0, v[174:175]
	global_load_lds_dwordx4 v[220:221], off
	v_lshl_add_u64 v[220:221], s[76:77], 0, v[176:177]
	s_add_i32 m0, s78, 0x2000
	s_nop 0
	global_load_lds_dwordx4 v[220:221], off
	v_lshl_add_u64 v[220:221], s[42:43], 0, v[170:171]
	s_mov_b32 m0, s19
	s_nop 0
	global_load_lds_dwordx4 v[220:221], off
	s_mov_b32 m0, s44
	s_nop 0
	global_load_lds_dwordx4 v[222:223], off
	s_waitcnt vmcnt(8)
	s_waitcnt lgkmcnt(0)
	s_barrier
	v_mfma_f32_16x16x32_bf16 v[62:65], v[130:133], v[162:165], v[62:65]
	v_mfma_f32_16x16x32_bf16 v[58:61], v[138:141], v[162:165], v[58:61]
	v_mfma_f32_16x16x32_bf16 v[46:49], v[130:133], v[186:189], v[46:49]
	v_mfma_f32_16x16x32_bf16 v[42:45], v[138:141], v[186:189], v[42:45]
	v_mfma_f32_16x16x32_bf16 v[30:33], v[130:133], v[194:197], v[30:33]
	v_mfma_f32_16x16x32_bf16 v[26:29], v[138:141], v[194:197], v[26:29]
	v_mfma_f32_16x16x32_bf16 v[14:17], v[130:133], v[202:205], v[14:17]
	v_mfma_f32_16x16x32_bf16 v[10:13], v[138:141], v[202:205], v[10:13]
	v_mfma_f32_16x16x32_bf16 v[62:65], v[134:137], v[166:169], v[62:65]
	v_mfma_f32_16x16x32_bf16 v[58:61], v[142:145], v[166:169], v[58:61]
	v_mfma_f32_16x16x32_bf16 v[46:49], v[134:137], v[190:193], v[46:49]
	v_mfma_f32_16x16x32_bf16 v[42:45], v[142:145], v[190:193], v[42:45]
	v_mfma_f32_16x16x32_bf16 v[30:33], v[134:137], v[198:201], v[30:33]
	v_mfma_f32_16x16x32_bf16 v[26:29], v[142:145], v[198:201], v[26:29]
	v_mfma_f32_16x16x32_bf16 v[14:17], v[134:137], v[206:209], v[14:17]
	v_mfma_f32_16x16x32_bf16 v[10:13], v[142:145], v[206:209], v[10:13]
	v_mfma_f32_16x16x32_bf16 v[54:57], v[146:149], v[162:165], v[54:57]
	v_mfma_f32_16x16x32_bf16 v[50:53], v[154:157], v[162:165], v[50:53]
	v_mfma_f32_16x16x32_bf16 v[38:41], v[146:149], v[186:189], v[38:41]
	v_mfma_f32_16x16x32_bf16 v[34:37], v[154:157], v[186:189], v[34:37]
	v_mfma_f32_16x16x32_bf16 v[22:25], v[146:149], v[194:197], v[22:25]
	v_mfma_f32_16x16x32_bf16 v[18:21], v[154:157], v[194:197], v[18:21]
	v_mfma_f32_16x16x32_bf16 v[6:9], v[146:149], v[202:205], v[6:9]
	v_mfma_f32_16x16x32_bf16 v[2:5], v[154:157], v[202:205], v[2:5]
	v_mfma_f32_16x16x32_bf16 v[54:57], v[150:153], v[166:169], v[54:57]
	v_mfma_f32_16x16x32_bf16 v[50:53], v[158:161], v[166:169], v[50:53]
	v_mfma_f32_16x16x32_bf16 v[38:41], v[150:153], v[190:193], v[38:41]
	v_mfma_f32_16x16x32_bf16 v[34:37], v[158:161], v[190:193], v[34:37]
	v_mfma_f32_16x16x32_bf16 v[22:25], v[150:153], v[198:201], v[22:25]
	v_mfma_f32_16x16x32_bf16 v[18:21], v[158:161], v[198:201], v[18:21]
	v_mfma_f32_16x16x32_bf16 v[6:9], v[150:153], v[206:209], v[6:9]
	v_mfma_f32_16x16x32_bf16 v[2:5], v[158:161], v[206:209], v[2:5]
	s_barrier
	s_add_i32 s76, 0, 0x18000
	s_add_i32 s77, 0, 0x1c000
	v_add_u32_e32 v142, s76, v211
	v_add_u32_e32 v158, s77, v211
	ds_read_b128 v[130:133], v142
	ds_read_b128 v[134:137], v142 offset:1024
	ds_read_b128 v[138:141], v142 offset:2048
	ds_read_b128 v[142:145], v142 offset:3072
	ds_read_b128 v[146:149], v158
	ds_read_b128 v[150:153], v158 offset:1024
	ds_read_b128 v[154:157], v158 offset:2048
	ds_read_b128 v[158:161], v158 offset:3072
	s_add_u32 s42, s42, 0x100000
	s_addc_u32 s43, s43, 0
	s_mov_b32 m0, s45
	v_lshl_add_u64 v[224:225], s[42:43], 0, v[170:171]
	ds_read_b128 v[162:165], v214 offset:32768
	ds_read_b128 v[166:169], v214 offset:33792
	ds_read_b128 v[186:189], v214 offset:34816
	ds_read_b128 v[190:193], v214 offset:35840
	ds_read_b128 v[194:197], v214 offset:36864
	ds_read_b128 v[198:201], v214 offset:37888
	ds_read_b128 v[202:205], v214 offset:38912
	ds_read_b128 v[206:209], v214 offset:39936
	global_load_lds_dwordx4 v[224:225], off
	v_lshl_add_u64 v[224:225], s[42:43], 0, v[174:175]
	s_mov_b32 m0, s46
	s_nop 0
	global_load_lds_dwordx4 v[224:225], off
	s_waitcnt vmcnt(8)
	s_waitcnt lgkmcnt(0)
	s_barrier
	v_mfma_f32_16x16x32_bf16 v[126:129], v[130:133], v[162:165], v[126:129]
	v_mfma_f32_16x16x32_bf16 v[122:125], v[138:141], v[162:165], v[122:125]
	v_mfma_f32_16x16x32_bf16 v[110:113], v[130:133], v[186:189], v[110:113]
	v_mfma_f32_16x16x32_bf16 v[106:109], v[138:141], v[186:189], v[106:109]
	v_mfma_f32_16x16x32_bf16 v[94:97], v[130:133], v[194:197], v[94:97]
	v_mfma_f32_16x16x32_bf16 v[90:93], v[138:141], v[194:197], v[90:93]
	v_mfma_f32_16x16x32_bf16 v[78:81], v[130:133], v[202:205], v[78:81]
	v_mfma_f32_16x16x32_bf16 v[74:77], v[138:141], v[202:205], v[74:77]
	v_mfma_f32_16x16x32_bf16 v[126:129], v[134:137], v[166:169], v[126:129]
	v_mfma_f32_16x16x32_bf16 v[122:125], v[142:145], v[166:169], v[122:125]
	v_mfma_f32_16x16x32_bf16 v[110:113], v[134:137], v[190:193], v[110:113]
	v_mfma_f32_16x16x32_bf16 v[106:109], v[142:145], v[190:193], v[106:109]
	v_mfma_f32_16x16x32_bf16 v[94:97], v[134:137], v[198:201], v[94:97]
	v_mfma_f32_16x16x32_bf16 v[90:93], v[142:145], v[198:201], v[90:93]
	v_mfma_f32_16x16x32_bf16 v[78:81], v[134:137], v[206:209], v[78:81]
	v_mfma_f32_16x16x32_bf16 v[74:77], v[142:145], v[206:209], v[74:77]
	v_mfma_f32_16x16x32_bf16 v[118:121], v[146:149], v[162:165], v[118:121]
	v_mfma_f32_16x16x32_bf16 v[114:117], v[154:157], v[162:165], v[114:117]
	v_mfma_f32_16x16x32_bf16 v[102:105], v[146:149], v[186:189], v[102:105]
	v_mfma_f32_16x16x32_bf16 v[98:101], v[154:157], v[186:189], v[98:101]
	v_mfma_f32_16x16x32_bf16 v[86:89], v[146:149], v[194:197], v[86:89]
	v_mfma_f32_16x16x32_bf16 v[82:85], v[154:157], v[194:197], v[82:85]
	v_mfma_f32_16x16x32_bf16 v[70:73], v[146:149], v[202:205], v[70:73]
	v_mfma_f32_16x16x32_bf16 v[66:69], v[154:157], v[202:205], v[66:69]
	v_mfma_f32_16x16x32_bf16 v[118:121], v[150:153], v[166:169], v[118:121]
	v_mfma_f32_16x16x32_bf16 v[114:117], v[158:161], v[166:169], v[114:117]
	v_mfma_f32_16x16x32_bf16 v[102:105], v[150:153], v[190:193], v[102:105]
	v_mfma_f32_16x16x32_bf16 v[98:101], v[158:161], v[190:193], v[98:101]
	v_mfma_f32_16x16x32_bf16 v[86:89], v[150:153], v[198:201], v[86:89]
	v_mfma_f32_16x16x32_bf16 v[82:85], v[158:161], v[198:201], v[82:85]
	v_mfma_f32_16x16x32_bf16 v[70:73], v[150:153], v[206:209], v[70:73]
	v_mfma_f32_16x16x32_bf16 v[66:69], v[158:161], v[206:209], v[66:69]
	s_barrier
	s_add_i32 s42, s76, s17
	v_lshl_add_u64 v[216:217], v[216:217], 0, s[8:9]
	s_mov_b32 m0, s42
	ds_read_b128 v[162:165], v214 offset:49152
	ds_read_b128 v[166:169], v214 offset:50176
	ds_read_b128 v[186:189], v214 offset:51200
	ds_read_b128 v[190:193], v214 offset:52224
	ds_read_b128 v[194:197], v214 offset:53248
	ds_read_b128 v[198:201], v214 offset:54272
	ds_read_b128 v[202:205], v214 offset:55296
	ds_read_b128 v[206:209], v214 offset:56320
	global_load_lds_dwordx4 v[216:217], off
	s_add_i32 m0, s42, 0x2000
	s_add_u32 s40, s40, 0x100080
	v_lshl_add_u64 v[216:217], v[218:219], 0, s[8:9]
	s_addc_u32 s41, s41, 0
	s_add_i32 s42, s77, s17
	global_load_lds_dwordx4 v[216:217], off
	v_lshl_add_u64 v[216:217], s[40:41], 0, v[172:173]
	s_mov_b32 m0, s42
	s_nop 0
	global_load_lds_dwordx4 v[216:217], off
	v_lshl_add_u64 v[216:217], s[40:41], 0, v[176:177]
	s_add_i32 m0, s42, 0x2000
	s_nop 0
	global_load_lds_dwordx4 v[216:217], off
	v_lshl_add_u64 v[216:217], v[220:221], 0, s[8:9]
	s_mov_b32 m0, s50
	s_nop 0
	global_load_lds_dwordx4 v[216:217], off
	v_lshl_add_u64 v[216:217], v[222:223], 0, s[8:9]
	s_mov_b32 m0, s51
	s_nop 0
	global_load_lds_dwordx4 v[216:217], off
	s_waitcnt vmcnt(8)
	s_waitcnt lgkmcnt(0)
	s_barrier
	v_mfma_f32_16x16x32_bf16 v[62:65], v[130:133], v[162:165], v[62:65]
	v_mfma_f32_16x16x32_bf16 v[58:61], v[138:141], v[162:165], v[58:61]
	v_mfma_f32_16x16x32_bf16 v[46:49], v[130:133], v[186:189], v[46:49]
	v_mfma_f32_16x16x32_bf16 v[42:45], v[138:141], v[186:189], v[42:45]
	v_mfma_f32_16x16x32_bf16 v[30:33], v[130:133], v[194:197], v[30:33]
	v_mfma_f32_16x16x32_bf16 v[26:29], v[138:141], v[194:197], v[26:29]
	v_mfma_f32_16x16x32_bf16 v[14:17], v[130:133], v[202:205], v[14:17]
	v_mfma_f32_16x16x32_bf16 v[10:13], v[138:141], v[202:205], v[10:13]
	v_mfma_f32_16x16x32_bf16 v[62:65], v[134:137], v[166:169], v[62:65]
	v_mfma_f32_16x16x32_bf16 v[58:61], v[142:145], v[166:169], v[58:61]
	v_mfma_f32_16x16x32_bf16 v[46:49], v[134:137], v[190:193], v[46:49]
	v_mfma_f32_16x16x32_bf16 v[42:45], v[142:145], v[190:193], v[42:45]
	v_mfma_f32_16x16x32_bf16 v[30:33], v[134:137], v[198:201], v[30:33]
	v_mfma_f32_16x16x32_bf16 v[26:29], v[142:145], v[198:201], v[26:29]
	v_mfma_f32_16x16x32_bf16 v[14:17], v[134:137], v[206:209], v[14:17]
	v_mfma_f32_16x16x32_bf16 v[10:13], v[142:145], v[206:209], v[10:13]
	v_mfma_f32_16x16x32_bf16 v[54:57], v[146:149], v[162:165], v[54:57]
	v_mfma_f32_16x16x32_bf16 v[50:53], v[154:157], v[162:165], v[50:53]
	v_mfma_f32_16x16x32_bf16 v[38:41], v[146:149], v[186:189], v[38:41]
	v_mfma_f32_16x16x32_bf16 v[34:37], v[154:157], v[186:189], v[34:37]
	v_mfma_f32_16x16x32_bf16 v[22:25], v[146:149], v[194:197], v[22:25]
	v_mfma_f32_16x16x32_bf16 v[18:21], v[154:157], v[194:197], v[18:21]
	v_mfma_f32_16x16x32_bf16 v[6:9], v[146:149], v[202:205], v[6:9]
	v_mfma_f32_16x16x32_bf16 v[2:5], v[154:157], v[202:205], v[2:5]
	v_mfma_f32_16x16x32_bf16 v[54:57], v[150:153], v[166:169], v[54:57]
	v_mfma_f32_16x16x32_bf16 v[50:53], v[158:161], v[166:169], v[50:53]
	v_mfma_f32_16x16x32_bf16 v[38:41], v[150:153], v[190:193], v[38:41]
	v_mfma_f32_16x16x32_bf16 v[34:37], v[158:161], v[190:193], v[34:37]
	v_mfma_f32_16x16x32_bf16 v[22:25], v[150:153], v[198:201], v[22:25]
	v_mfma_f32_16x16x32_bf16 v[18:21], v[158:161], v[198:201], v[18:21]
	v_mfma_f32_16x16x32_bf16 v[6:9], v[150:153], v[206:209], v[6:9]
	v_mfma_f32_16x16x32_bf16 v[2:5], v[158:161], v[206:209], v[2:5]
	s_barrier
	s_add_i32 s73, s73, 2
	s_add_u32 s38, s38, 0x100
	s_addc_u32 s39, s39, 0
	s_add_u32 s71, s71, 0x100
	s_addc_u32 s72, s72, 0
	s_cmp_gt_u32 s73, 61
	s_cbranch_scc0 .LBB0_1921
	s_and_b64 vcc, exec, s[10:11]
	s_cbranch_vccz .LBB0_1924
	s_barrier

.LBB0_2056:
	ds_read_b128 v[130:133], v234
	ds_read_b128 v[134:137], v234 offset:1024
	ds_read_b128 v[162:165], v234 offset:2048
	ds_read_b128 v[166:169], v234 offset:3072
	ds_read_b128 v[170:173], v235
	ds_read_b128 v[174:177], v235 offset:1024
	ds_read_b128 v[178:181], v235 offset:2048
	ds_read_b128 v[182:185], v235 offset:3072
	s_add_u32 s4, s2, 0x100
	s_addc_u32 s5, s3, 0
	s_cmp_eq_u32 s93, 28
	s_cselect_b32 s43, s31, s5
	s_cselect_b32 s42, s87, s4
	s_cselect_b32 s19, s29, s92
	s_cselect_b32 s18, s90, s91
	v_lshl_add_u64 v[218:219], s[2:3], 0, v[154:155]
	s_add_i32 m0, s49, 0xc000
	ds_read_b128 v[186:189], v236
	ds_read_b128 v[190:193], v236 offset:1024
	ds_read_b128 v[194:197], v236 offset:2048
	ds_read_b128 v[198:201], v236 offset:3072
	ds_read_b128 v[202:205], v236 offset:4096
	ds_read_b128 v[206:209], v236 offset:5120
	ds_read_b128 v[210:213], v236 offset:6144
	ds_read_b128 v[214:217], v236 offset:7168
	global_load_lds_dwordx4 v[218:219], off
	v_lshl_add_u64 v[218:219], s[2:3], 0, v[156:157]
	s_add_i32 m0, s49, 0xe000
	s_nop 0
	global_load_lds_dwordx4 v[218:219], off
	s_waitcnt vmcnt(8)
	s_waitcnt lgkmcnt(0)
	s_barrier
	v_mfma_i32_16x16x64_i8 v[118:121], v[130:133], v[186:189], v[118:121]
	v_mfma_i32_16x16x64_i8 v[102:105], v[162:165], v[186:189], v[102:105]
	v_mfma_i32_16x16x64_i8 v[114:117], v[130:133], v[194:197], v[114:117]
	v_mfma_i32_16x16x64_i8 v[98:101], v[162:165], v[194:197], v[98:101]
	v_mfma_i32_16x16x64_i8 v[126:129], v[130:133], v[202:205], v[126:129]
	v_mfma_i32_16x16x64_i8 v[110:113], v[162:165], v[202:205], v[110:113]
	v_mfma_i32_16x16x64_i8 v[122:125], v[130:133], v[210:213], v[122:125]
	v_mfma_i32_16x16x64_i8 v[106:109], v[162:165], v[210:213], v[106:109]
	v_mfma_i32_16x16x64_i8 v[118:121], v[134:137], v[190:193], v[118:121]
	v_mfma_i32_16x16x64_i8 v[102:105], v[166:169], v[190:193], v[102:105]
	v_mfma_i32_16x16x64_i8 v[114:117], v[134:137], v[198:201], v[114:117]
	v_mfma_i32_16x16x64_i8 v[98:101], v[166:169], v[198:201], v[98:101]
	v_mfma_i32_16x16x64_i8 v[126:129], v[134:137], v[206:209], v[126:129]
	v_mfma_i32_16x16x64_i8 v[110:113], v[166:169], v[206:209], v[110:113]
	v_mfma_i32_16x16x64_i8 v[122:125], v[134:137], v[214:217], v[122:125]
	v_mfma_i32_16x16x64_i8 v[106:109], v[166:169], v[214:217], v[106:109]
	v_mfma_i32_16x16x64_i8 v[86:89], v[170:173], v[186:189], v[86:89]
	v_mfma_i32_16x16x64_i8 v[70:73], v[178:181], v[186:189], v[70:73]
	v_mfma_i32_16x16x64_i8 v[82:85], v[170:173], v[194:197], v[82:85]
	v_mfma_i32_16x16x64_i8 v[66:69], v[178:181], v[194:197], v[66:69]
	v_mfma_i32_16x16x64_i8 v[94:97], v[170:173], v[202:205], v[94:97]
	v_mfma_i32_16x16x64_i8 v[78:81], v[178:181], v[202:205], v[78:81]
	v_mfma_i32_16x16x64_i8 v[90:93], v[170:173], v[210:213], v[90:93]
	v_mfma_i32_16x16x64_i8 v[74:77], v[178:181], v[210:213], v[74:77]
	v_mfma_i32_16x16x64_i8 v[86:89], v[174:177], v[190:193], v[86:89]
	v_mfma_i32_16x16x64_i8 v[70:73], v[182:185], v[190:193], v[70:73]
	v_mfma_i32_16x16x64_i8 v[82:85], v[174:177], v[198:201], v[82:85]
	v_mfma_i32_16x16x64_i8 v[66:69], v[182:185], v[198:201], v[66:69]
	v_mfma_i32_16x16x64_i8 v[94:97], v[174:177], v[206:209], v[94:97]
	v_mfma_i32_16x16x64_i8 v[78:81], v[182:185], v[206:209], v[78:81]
	v_mfma_i32_16x16x64_i8 v[90:93], v[174:177], v[214:217], v[90:93]
	v_mfma_i32_16x16x64_i8 v[74:77], v[182:185], v[214:217], v[74:77]
	s_barrier
	s_add_i32 s2, s82, s47
	v_lshl_add_u64 v[218:219], s[18:19], 0, v[144:145]
	s_mov_b32 m0, s2
	ds_read_b128 v[186:189], v236 offset:16384
	ds_read_b128 v[190:193], v236 offset:17408
	ds_read_b128 v[194:197], v236 offset:18432
	ds_read_b128 v[198:201], v236 offset:19456
	ds_read_b128 v[202:205], v236 offset:20480
	ds_read_b128 v[206:209], v236 offset:21504
	ds_read_b128 v[210:213], v236 offset:22528
	ds_read_b128 v[214:217], v236 offset:23552
	global_load_lds_dwordx4 v[218:219], off
	s_add_i32 m0, s2, 0x2000
	s_add_u32 s2, s18, 0x80000
	v_lshl_add_u64 v[220:221], s[18:19], 0, v[148:149]
	s_addc_u32 s3, s19, 0
	s_add_i32 s94, s16, s47
	global_load_lds_dwordx4 v[220:221], off
	v_lshl_add_u64 v[222:223], s[2:3], 0, v[144:145]
	s_mov_b32 m0, s94
	v_lshl_add_u64 v[224:225], s[42:43], 0, v[146:147]
	global_load_lds_dwordx4 v[222:223], off
	v_lshl_add_u64 v[222:223], s[2:3], 0, v[148:149]
	s_add_i32 m0, s94, 0x2000
	s_nop 0
	global_load_lds_dwordx4 v[222:223], off
	v_lshl_add_u64 v[222:223], s[42:43], 0, v[142:143]
	s_mov_b32 m0, s49
	s_nop 0
	global_load_lds_dwordx4 v[222:223], off
	s_mov_b32 m0, s50
	s_nop 0
	global_load_lds_dwordx4 v[224:225], off
	s_waitcnt vmcnt(8)
	s_waitcnt lgkmcnt(0)
	s_barrier
	v_mfma_i32_16x16x64_i8 v[54:57], v[130:133], v[186:189], v[54:57]
	v_mfma_i32_16x16x64_i8 v[18:21], v[162:165], v[186:189], v[18:21]
	v_mfma_i32_16x16x64_i8 v[50:53], v[130:133], v[194:197], v[50:53]
	v_mfma_i32_16x16x64_i8 v[22:25], v[162:165], v[194:197], v[22:25]
	v_mfma_i32_16x16x64_i8 v[62:65], v[130:133], v[202:205], v[62:65]
	v_mfma_i32_16x16x64_i8 v[30:33], v[162:165], v[202:205], v[30:33]
	v_mfma_i32_16x16x64_i8 v[58:61], v[130:133], v[210:213], v[58:61]
	v_mfma_i32_16x16x64_i8 v[26:29], v[162:165], v[210:213], v[26:29]
	v_mfma_i32_16x16x64_i8 v[54:57], v[134:137], v[190:193], v[54:57]
	v_mfma_i32_16x16x64_i8 v[18:21], v[166:169], v[190:193], v[18:21]
	v_mfma_i32_16x16x64_i8 v[50:53], v[134:137], v[198:201], v[50:53]
	v_mfma_i32_16x16x64_i8 v[22:25], v[166:169], v[198:201], v[22:25]
	v_mfma_i32_16x16x64_i8 v[62:65], v[134:137], v[206:209], v[62:65]
	v_mfma_i32_16x16x64_i8 v[30:33], v[166:169], v[206:209], v[30:33]
	v_mfma_i32_16x16x64_i8 v[58:61], v[134:137], v[214:217], v[58:61]
	v_mfma_i32_16x16x64_i8 v[26:29], v[166:169], v[214:217], v[26:29]
	v_mfma_i32_16x16x64_i8 v[46:49], v[170:173], v[186:189], v[46:49]
	v_mfma_i32_16x16x64_i8 v[14:17], v[178:181], v[186:189], v[14:17]
	v_mfma_i32_16x16x64_i8 v[42:45], v[170:173], v[194:197], v[42:45]
	v_mfma_i32_16x16x64_i8 v[10:13], v[178:181], v[194:197], v[10:13]
	v_mfma_i32_16x16x64_i8 v[38:41], v[170:173], v[202:205], v[38:41]
	v_mfma_i32_16x16x64_i8 v[6:9], v[178:181], v[202:205], v[6:9]
	v_mfma_i32_16x16x64_i8 v[34:37], v[170:173], v[210:213], v[34:37]
	v_mfma_i32_16x16x64_i8 v[2:5], v[178:181], v[210:213], v[2:5]
	v_mfma_i32_16x16x64_i8 v[46:49], v[174:177], v[190:193], v[46:49]
	v_mfma_i32_16x16x64_i8 v[14:17], v[182:185], v[190:193], v[14:17]
	v_mfma_i32_16x16x64_i8 v[42:45], v[174:177], v[198:201], v[42:45]
	v_mfma_i32_16x16x64_i8 v[10:13], v[182:185], v[198:201], v[10:13]
	v_mfma_i32_16x16x64_i8 v[38:41], v[174:177], v[206:209], v[38:41]
	v_mfma_i32_16x16x64_i8 v[6:9], v[182:185], v[206:209], v[6:9]
	v_mfma_i32_16x16x64_i8 v[34:37], v[174:177], v[214:217], v[34:37]
	v_mfma_i32_16x16x64_i8 v[2:5], v[182:185], v[214:217], v[2:5]
	s_barrier
	s_add_i32 s94, 0, 0x18000
	s_add_i32 s95, 0, 0x1c000
	v_add_u32_e32 v166, s94, v232
	v_add_u32_e32 v182, s95, v232
	ds_read_b128 v[130:133], v166
	ds_read_b128 v[134:137], v166 offset:1024
	ds_read_b128 v[162:165], v166 offset:2048
	ds_read_b128 v[166:169], v166 offset:3072
	ds_read_b128 v[170:173], v182
	ds_read_b128 v[174:177], v182 offset:1024
	ds_read_b128 v[178:181], v182 offset:2048
	ds_read_b128 v[182:185], v182 offset:3072
	s_add_u32 s2, s42, 0x80000
	s_addc_u32 s3, s43, 0
	s_mov_b32 m0, s51
	v_lshl_add_u64 v[226:227], s[2:3], 0, v[142:143]
	ds_read_b128 v[186:189], v236 offset:32768
	ds_read_b128 v[190:193], v236 offset:33792
	ds_read_b128 v[194:197], v236 offset:34816
	ds_read_b128 v[198:201], v236 offset:35840
	ds_read_b128 v[202:205], v236 offset:36864
	ds_read_b128 v[206:209], v236 offset:37888
	ds_read_b128 v[210:213], v236 offset:38912
	ds_read_b128 v[214:217], v236 offset:39936
	global_load_lds_dwordx4 v[226:227], off
	v_lshl_add_u64 v[226:227], s[2:3], 0, v[146:147]
	s_mov_b32 m0, s54
	s_nop 0
	global_load_lds_dwordx4 v[226:227], off
	s_waitcnt vmcnt(8)
	s_waitcnt lgkmcnt(0)
	s_barrier
	v_mfma_i32_16x16x64_i8 v[118:121], v[130:133], v[186:189], v[118:121]
	v_mfma_i32_16x16x64_i8 v[102:105], v[162:165], v[186:189], v[102:105]
	v_mfma_i32_16x16x64_i8 v[114:117], v[130:133], v[194:197], v[114:117]
	v_mfma_i32_16x16x64_i8 v[98:101], v[162:165], v[194:197], v[98:101]
	v_mfma_i32_16x16x64_i8 v[126:129], v[130:133], v[202:205], v[126:129]
	v_mfma_i32_16x16x64_i8 v[110:113], v[162:165], v[202:205], v[110:113]
	v_mfma_i32_16x16x64_i8 v[122:125], v[130:133], v[210:213], v[122:125]
	v_mfma_i32_16x16x64_i8 v[106:109], v[162:165], v[210:213], v[106:109]
	v_mfma_i32_16x16x64_i8 v[118:121], v[134:137], v[190:193], v[118:121]
	v_mfma_i32_16x16x64_i8 v[102:105], v[166:169], v[190:193], v[102:105]
	v_mfma_i32_16x16x64_i8 v[114:117], v[134:137], v[198:201], v[114:117]
	v_mfma_i32_16x16x64_i8 v[98:101], v[166:169], v[198:201], v[98:101]
	v_mfma_i32_16x16x64_i8 v[126:129], v[134:137], v[206:209], v[126:129]
	v_mfma_i32_16x16x64_i8 v[110:113], v[166:169], v[206:209], v[110:113]
	v_mfma_i32_16x16x64_i8 v[122:125], v[134:137], v[214:217], v[122:125]
	v_mfma_i32_16x16x64_i8 v[106:109], v[166:169], v[214:217], v[106:109]
	v_mfma_i32_16x16x64_i8 v[86:89], v[170:173], v[186:189], v[86:89]
	v_mfma_i32_16x16x64_i8 v[70:73], v[178:181], v[186:189], v[70:73]
	v_mfma_i32_16x16x64_i8 v[82:85], v[170:173], v[194:197], v[82:85]
	v_mfma_i32_16x16x64_i8 v[66:69], v[178:181], v[194:197], v[66:69]
	v_mfma_i32_16x16x64_i8 v[94:97], v[170:173], v[202:205], v[94:97]
	v_mfma_i32_16x16x64_i8 v[78:81], v[178:181], v[202:205], v[78:81]
	v_mfma_i32_16x16x64_i8 v[90:93], v[170:173], v[210:213], v[90:93]
	v_mfma_i32_16x16x64_i8 v[74:77], v[178:181], v[210:213], v[74:77]
	v_mfma_i32_16x16x64_i8 v[86:89], v[174:177], v[190:193], v[86:89]
	v_mfma_i32_16x16x64_i8 v[70:73], v[182:185], v[190:193], v[70:73]
	v_mfma_i32_16x16x64_i8 v[82:85], v[174:177], v[198:201], v[82:85]
	v_mfma_i32_16x16x64_i8 v[66:69], v[182:185], v[198:201], v[66:69]
	v_mfma_i32_16x16x64_i8 v[94:97], v[174:177], v[206:209], v[94:97]
	v_mfma_i32_16x16x64_i8 v[78:81], v[182:185], v[206:209], v[78:81]
	v_mfma_i32_16x16x64_i8 v[90:93], v[174:177], v[214:217], v[90:93]
	v_mfma_i32_16x16x64_i8 v[74:77], v[182:185], v[214:217], v[74:77]
	s_barrier
	s_add_i32 s2, s94, s47
	v_lshl_add_u64 v[218:219], v[218:219], 0, s[14:15]
	s_mov_b32 m0, s2
	ds_read_b128 v[186:189], v236 offset:49152
	ds_read_b128 v[190:193], v236 offset:50176
	ds_read_b128 v[194:197], v236 offset:51200
	ds_read_b128 v[198:201], v236 offset:52224
	ds_read_b128 v[202:205], v236 offset:53248
	ds_read_b128 v[206:209], v236 offset:54272
	ds_read_b128 v[210:213], v236 offset:55296
	ds_read_b128 v[214:217], v236 offset:56320
	global_load_lds_dwordx4 v[218:219], off
	s_add_i32 m0, s2, 0x2000
	s_add_u32 s2, s18, 0x80080
	v_lshl_add_u64 v[218:219], v[220:221], 0, s[14:15]
	s_addc_u32 s3, s19, 0
	s_add_i32 s18, s95, s47
	global_load_lds_dwordx4 v[218:219], off
	v_lshl_add_u64 v[218:219], s[2:3], 0, v[144:145]
	s_mov_b32 m0, s18
	s_nop 0
	global_load_lds_dwordx4 v[218:219], off
	v_lshl_add_u64 v[218:219], s[2:3], 0, v[148:149]
	s_add_i32 m0, s18, 0x2000
	s_nop 0
	global_load_lds_dwordx4 v[218:219], off
	v_lshl_add_u64 v[218:219], v[222:223], 0, s[14:15]
	s_mov_b32 m0, s63
	s_nop 0
	global_load_lds_dwordx4 v[218:219], off
	v_lshl_add_u64 v[218:219], v[224:225], 0, s[14:15]
	s_mov_b32 m0, s64
	s_nop 0
	global_load_lds_dwordx4 v[218:219], off
	s_waitcnt vmcnt(8)
	s_waitcnt lgkmcnt(0)
	s_barrier
	v_mfma_i32_16x16x64_i8 v[54:57], v[130:133], v[186:189], v[54:57]
	v_mfma_i32_16x16x64_i8 v[18:21], v[162:165], v[186:189], v[18:21]
	v_mfma_i32_16x16x64_i8 v[50:53], v[130:133], v[194:197], v[50:53]
	v_mfma_i32_16x16x64_i8 v[22:25], v[162:165], v[194:197], v[22:25]
	v_mfma_i32_16x16x64_i8 v[62:65], v[130:133], v[202:205], v[62:65]
	v_mfma_i32_16x16x64_i8 v[30:33], v[162:165], v[202:205], v[30:33]
	v_mfma_i32_16x16x64_i8 v[58:61], v[130:133], v[210:213], v[58:61]
	v_mfma_i32_16x16x64_i8 v[26:29], v[162:165], v[210:213], v[26:29]
	v_mfma_i32_16x16x64_i8 v[54:57], v[134:137], v[190:193], v[54:57]
	v_mfma_i32_16x16x64_i8 v[18:21], v[166:169], v[190:193], v[18:21]
	v_mfma_i32_16x16x64_i8 v[50:53], v[134:137], v[198:201], v[50:53]
	v_mfma_i32_16x16x64_i8 v[22:25], v[166:169], v[198:201], v[22:25]
	v_mfma_i32_16x16x64_i8 v[62:65], v[134:137], v[206:209], v[62:65]
	v_mfma_i32_16x16x64_i8 v[30:33], v[166:169], v[206:209], v[30:33]
	v_mfma_i32_16x16x64_i8 v[58:61], v[134:137], v[214:217], v[58:61]
	v_mfma_i32_16x16x64_i8 v[26:29], v[166:169], v[214:217], v[26:29]
	v_mfma_i32_16x16x64_i8 v[46:49], v[170:173], v[186:189], v[46:49]
	v_mfma_i32_16x16x64_i8 v[14:17], v[178:181], v[186:189], v[14:17]
	v_mfma_i32_16x16x64_i8 v[42:45], v[170:173], v[194:197], v[42:45]
	v_mfma_i32_16x16x64_i8 v[10:13], v[178:181], v[194:197], v[10:13]
	v_mfma_i32_16x16x64_i8 v[38:41], v[170:173], v[202:205], v[38:41]
	v_mfma_i32_16x16x64_i8 v[6:9], v[178:181], v[202:205], v[6:9]
	v_mfma_i32_16x16x64_i8 v[34:37], v[170:173], v[210:213], v[34:37]
	v_mfma_i32_16x16x64_i8 v[2:5], v[178:181], v[210:213], v[2:5]
	v_mfma_i32_16x16x64_i8 v[46:49], v[174:177], v[190:193], v[46:49]
	v_mfma_i32_16x16x64_i8 v[14:17], v[182:185], v[190:193], v[14:17]
	v_mfma_i32_16x16x64_i8 v[42:45], v[174:177], v[198:201], v[42:45]
	v_mfma_i32_16x16x64_i8 v[10:13], v[182:185], v[198:201], v[10:13]
	v_mfma_i32_16x16x64_i8 v[38:41], v[174:177], v[206:209], v[38:41]
	v_mfma_i32_16x16x64_i8 v[6:9], v[182:185], v[206:209], v[6:9]
	v_mfma_i32_16x16x64_i8 v[34:37], v[174:177], v[214:217], v[34:37]
	v_mfma_i32_16x16x64_i8 v[2:5], v[182:185], v[214:217], v[2:5]
	s_barrier
	s_add_i32 s93, s93, 2
	s_add_u32 s91, s91, 0x100
	s_addc_u32 s92, s92, 0
	s_cmp_gt_u32 s93, 29
	s_mov_b64 s[2:3], s[4:5]
	s_cbranch_scc0 .LBB0_2056
	s_and_b64 vcc, exec, s[8:9]
	s_cbranch_vccz .LBB0_2059
	s_barrier

.LBB0_2241:
	ds_read_b128 v[130:133], v212
	ds_read_b128 v[134:137], v212 offset:1024
	ds_read_b128 v[138:141], v212 offset:2048
	ds_read_b128 v[142:145], v212 offset:3072
	ds_read_b128 v[146:149], v213
	ds_read_b128 v[150:153], v213 offset:1024
	ds_read_b128 v[154:157], v213 offset:2048
	ds_read_b128 v[158:161], v213 offset:3072
	s_add_u32 s36, s18, 0x100
	s_addc_u32 s37, s19, 0
	s_cmpk_eq_i32 s71, 0xdc
	s_cselect_b32 s41, s3, s37
	s_cselect_b32 s40, s2, s36
	s_cselect_b32 s39, s35, s70
	s_cselect_b32 s38, s34, s69
	v_lshl_add_u64 v[216:217], s[18:19], 0, v[178:179]
	s_add_i32 m0, s44, 0xc000
	ds_read_b128 v[162:165], v214
	ds_read_b128 v[166:169], v214 offset:1024
	ds_read_b128 v[186:189], v214 offset:2048
	ds_read_b128 v[190:193], v214 offset:3072
	ds_read_b128 v[194:197], v214 offset:4096
	ds_read_b128 v[198:201], v214 offset:5120
	ds_read_b128 v[202:205], v214 offset:6144
	ds_read_b128 v[206:209], v214 offset:7168
	global_load_lds_dwordx4 v[216:217], off
	v_lshl_add_u64 v[216:217], s[18:19], 0, v[180:181]
	s_add_i32 m0, s44, 0xe000
	s_nop 0
	global_load_lds_dwordx4 v[216:217], off
	s_waitcnt vmcnt(8)
	s_waitcnt lgkmcnt(0)
	s_barrier
	v_mfma_f32_16x16x32_bf16 v[126:129], v[130:133], v[162:165], v[126:129]
	v_mfma_f32_16x16x32_bf16 v[122:125], v[138:141], v[162:165], v[122:125]
	v_mfma_f32_16x16x32_bf16 v[110:113], v[130:133], v[186:189], v[110:113]
	v_mfma_f32_16x16x32_bf16 v[106:109], v[138:141], v[186:189], v[106:109]
	v_mfma_f32_16x16x32_bf16 v[94:97], v[130:133], v[194:197], v[94:97]
	v_mfma_f32_16x16x32_bf16 v[90:93], v[138:141], v[194:197], v[90:93]
	v_mfma_f32_16x16x32_bf16 v[78:81], v[130:133], v[202:205], v[78:81]
	v_mfma_f32_16x16x32_bf16 v[74:77], v[138:141], v[202:205], v[74:77]
	v_mfma_f32_16x16x32_bf16 v[126:129], v[134:137], v[166:169], v[126:129]
	v_mfma_f32_16x16x32_bf16 v[122:125], v[142:145], v[166:169], v[122:125]
	v_mfma_f32_16x16x32_bf16 v[110:113], v[134:137], v[190:193], v[110:113]
	v_mfma_f32_16x16x32_bf16 v[106:109], v[142:145], v[190:193], v[106:109]
	v_mfma_f32_16x16x32_bf16 v[94:97], v[134:137], v[198:201], v[94:97]
	v_mfma_f32_16x16x32_bf16 v[90:93], v[142:145], v[198:201], v[90:93]
	v_mfma_f32_16x16x32_bf16 v[78:81], v[134:137], v[206:209], v[78:81]
	v_mfma_f32_16x16x32_bf16 v[74:77], v[142:145], v[206:209], v[74:77]
	v_mfma_f32_16x16x32_bf16 v[118:121], v[146:149], v[162:165], v[118:121]
	v_mfma_f32_16x16x32_bf16 v[114:117], v[154:157], v[162:165], v[114:117]
	v_mfma_f32_16x16x32_bf16 v[102:105], v[146:149], v[186:189], v[102:105]
	v_mfma_f32_16x16x32_bf16 v[98:101], v[154:157], v[186:189], v[98:101]
	v_mfma_f32_16x16x32_bf16 v[86:89], v[146:149], v[194:197], v[86:89]
	v_mfma_f32_16x16x32_bf16 v[82:85], v[154:157], v[194:197], v[82:85]
	v_mfma_f32_16x16x32_bf16 v[70:73], v[146:149], v[202:205], v[70:73]
	v_mfma_f32_16x16x32_bf16 v[66:69], v[154:157], v[202:205], v[66:69]
	v_mfma_f32_16x16x32_bf16 v[118:121], v[150:153], v[166:169], v[118:121]
	v_mfma_f32_16x16x32_bf16 v[114:117], v[158:161], v[166:169], v[114:117]
	v_mfma_f32_16x16x32_bf16 v[102:105], v[150:153], v[190:193], v[102:105]
	v_mfma_f32_16x16x32_bf16 v[98:101], v[158:161], v[190:193], v[98:101]
	v_mfma_f32_16x16x32_bf16 v[86:89], v[150:153], v[198:201], v[86:89]
	v_mfma_f32_16x16x32_bf16 v[82:85], v[158:161], v[198:201], v[82:85]
	v_mfma_f32_16x16x32_bf16 v[70:73], v[150:153], v[206:209], v[70:73]
	v_mfma_f32_16x16x32_bf16 v[66:69], v[158:161], v[206:209], v[66:69]
	s_barrier
	s_add_i32 s18, s56, s43
	v_lshl_add_u64 v[216:217], s[38:39], 0, v[172:173]
	s_mov_b32 m0, s18
	ds_read_b128 v[162:165], v214 offset:16384
	ds_read_b128 v[166:169], v214 offset:17408
	ds_read_b128 v[186:189], v214 offset:18432
	ds_read_b128 v[190:193], v214 offset:19456
	ds_read_b128 v[194:197], v214 offset:20480
	ds_read_b128 v[198:201], v214 offset:21504
	ds_read_b128 v[202:205], v214 offset:22528
	ds_read_b128 v[206:209], v214 offset:23552
	global_load_lds_dwordx4 v[216:217], off
	s_add_i32 m0, s18, 0x2000
	s_add_u32 s18, s38, 0x380000
	v_lshl_add_u64 v[218:219], s[38:39], 0, v[176:177]
	s_addc_u32 s19, s39, 0
	s_add_i32 s72, s57, s43
	global_load_lds_dwordx4 v[218:219], off
	v_lshl_add_u64 v[220:221], s[18:19], 0, v[172:173]
	s_mov_b32 m0, s72
	v_lshl_add_u64 v[222:223], s[40:41], 0, v[174:175]
	global_load_lds_dwordx4 v[220:221], off
	v_lshl_add_u64 v[220:221], s[18:19], 0, v[176:177]
	s_add_i32 m0, s72, 0x2000
	s_nop 0
	global_load_lds_dwordx4 v[220:221], off
	v_lshl_add_u64 v[220:221], s[40:41], 0, v[170:171]
	s_mov_b32 m0, s44
	s_nop 0
	global_load_lds_dwordx4 v[220:221], off
	s_mov_b32 m0, s45
	s_nop 0
	global_load_lds_dwordx4 v[222:223], off
	s_waitcnt vmcnt(8)
	s_waitcnt lgkmcnt(0)
	s_barrier
	v_mfma_f32_16x16x32_bf16 v[62:65], v[130:133], v[162:165], v[62:65]
	v_mfma_f32_16x16x32_bf16 v[58:61], v[138:141], v[162:165], v[58:61]
	v_mfma_f32_16x16x32_bf16 v[46:49], v[130:133], v[186:189], v[46:49]
	v_mfma_f32_16x16x32_bf16 v[42:45], v[138:141], v[186:189], v[42:45]
	v_mfma_f32_16x16x32_bf16 v[30:33], v[130:133], v[194:197], v[30:33]
	v_mfma_f32_16x16x32_bf16 v[26:29], v[138:141], v[194:197], v[26:29]
	v_mfma_f32_16x16x32_bf16 v[14:17], v[130:133], v[202:205], v[14:17]
	v_mfma_f32_16x16x32_bf16 v[10:13], v[138:141], v[202:205], v[10:13]
	v_mfma_f32_16x16x32_bf16 v[62:65], v[134:137], v[166:169], v[62:65]
	v_mfma_f32_16x16x32_bf16 v[58:61], v[142:145], v[166:169], v[58:61]
	v_mfma_f32_16x16x32_bf16 v[46:49], v[134:137], v[190:193], v[46:49]
	v_mfma_f32_16x16x32_bf16 v[42:45], v[142:145], v[190:193], v[42:45]
	v_mfma_f32_16x16x32_bf16 v[30:33], v[134:137], v[198:201], v[30:33]
	v_mfma_f32_16x16x32_bf16 v[26:29], v[142:145], v[198:201], v[26:29]
	v_mfma_f32_16x16x32_bf16 v[14:17], v[134:137], v[206:209], v[14:17]
	v_mfma_f32_16x16x32_bf16 v[10:13], v[142:145], v[206:209], v[10:13]
	v_mfma_f32_16x16x32_bf16 v[54:57], v[146:149], v[162:165], v[54:57]
	v_mfma_f32_16x16x32_bf16 v[50:53], v[154:157], v[162:165], v[50:53]
	v_mfma_f32_16x16x32_bf16 v[38:41], v[146:149], v[186:189], v[38:41]
	v_mfma_f32_16x16x32_bf16 v[34:37], v[154:157], v[186:189], v[34:37]
	v_mfma_f32_16x16x32_bf16 v[22:25], v[146:149], v[194:197], v[22:25]
	v_mfma_f32_16x16x32_bf16 v[18:21], v[154:157], v[194:197], v[18:21]
	v_mfma_f32_16x16x32_bf16 v[6:9], v[146:149], v[202:205], v[6:9]
	v_mfma_f32_16x16x32_bf16 v[2:5], v[154:157], v[202:205], v[2:5]
	v_mfma_f32_16x16x32_bf16 v[54:57], v[150:153], v[166:169], v[54:57]
	v_mfma_f32_16x16x32_bf16 v[50:53], v[158:161], v[166:169], v[50:53]
	v_mfma_f32_16x16x32_bf16 v[38:41], v[150:153], v[190:193], v[38:41]
	v_mfma_f32_16x16x32_bf16 v[34:37], v[158:161], v[190:193], v[34:37]
	v_mfma_f32_16x16x32_bf16 v[22:25], v[150:153], v[198:201], v[22:25]
	v_mfma_f32_16x16x32_bf16 v[18:21], v[158:161], v[198:201], v[18:21]
	v_mfma_f32_16x16x32_bf16 v[6:9], v[150:153], v[206:209], v[6:9]
	v_mfma_f32_16x16x32_bf16 v[2:5], v[158:161], v[206:209], v[2:5]
	s_barrier
	s_add_i32 s72, 0, 0x18000
	s_add_i32 s73, 0, 0x1c000
	v_add_u32_e32 v142, s72, v211
	v_add_u32_e32 v158, s73, v211
	ds_read_b128 v[130:133], v142
	ds_read_b128 v[134:137], v142 offset:1024
	ds_read_b128 v[138:141], v142 offset:2048
	ds_read_b128 v[142:145], v142 offset:3072
	ds_read_b128 v[146:149], v158
	ds_read_b128 v[150:153], v158 offset:1024
	ds_read_b128 v[154:157], v158 offset:2048
	ds_read_b128 v[158:161], v158 offset:3072
	s_add_u32 s18, s40, 0x380000
	s_addc_u32 s19, s41, 0
	s_mov_b32 m0, s46
	v_lshl_add_u64 v[224:225], s[18:19], 0, v[170:171]
	ds_read_b128 v[162:165], v214 offset:32768
	ds_read_b128 v[166:169], v214 offset:33792
	ds_read_b128 v[186:189], v214 offset:34816
	ds_read_b128 v[190:193], v214 offset:35840
	ds_read_b128 v[194:197], v214 offset:36864
	ds_read_b128 v[198:201], v214 offset:37888
	ds_read_b128 v[202:205], v214 offset:38912
	ds_read_b128 v[206:209], v214 offset:39936
	global_load_lds_dwordx4 v[224:225], off
	v_lshl_add_u64 v[224:225], s[18:19], 0, v[174:175]
	s_mov_b32 m0, s47
	s_nop 0
	global_load_lds_dwordx4 v[224:225], off
	s_waitcnt vmcnt(8)
	s_waitcnt lgkmcnt(0)
	s_barrier
	v_mfma_f32_16x16x32_bf16 v[126:129], v[130:133], v[162:165], v[126:129]
	v_mfma_f32_16x16x32_bf16 v[122:125], v[138:141], v[162:165], v[122:125]
	v_mfma_f32_16x16x32_bf16 v[110:113], v[130:133], v[186:189], v[110:113]
	v_mfma_f32_16x16x32_bf16 v[106:109], v[138:141], v[186:189], v[106:109]
	v_mfma_f32_16x16x32_bf16 v[94:97], v[130:133], v[194:197], v[94:97]
	v_mfma_f32_16x16x32_bf16 v[90:93], v[138:141], v[194:197], v[90:93]
	v_mfma_f32_16x16x32_bf16 v[78:81], v[130:133], v[202:205], v[78:81]
	v_mfma_f32_16x16x32_bf16 v[74:77], v[138:141], v[202:205], v[74:77]
	v_mfma_f32_16x16x32_bf16 v[126:129], v[134:137], v[166:169], v[126:129]
	v_mfma_f32_16x16x32_bf16 v[122:125], v[142:145], v[166:169], v[122:125]
	v_mfma_f32_16x16x32_bf16 v[110:113], v[134:137], v[190:193], v[110:113]
	v_mfma_f32_16x16x32_bf16 v[106:109], v[142:145], v[190:193], v[106:109]
	v_mfma_f32_16x16x32_bf16 v[94:97], v[134:137], v[198:201], v[94:97]
	v_mfma_f32_16x16x32_bf16 v[90:93], v[142:145], v[198:201], v[90:93]
	v_mfma_f32_16x16x32_bf16 v[78:81], v[134:137], v[206:209], v[78:81]
	v_mfma_f32_16x16x32_bf16 v[74:77], v[142:145], v[206:209], v[74:77]
	v_mfma_f32_16x16x32_bf16 v[118:121], v[146:149], v[162:165], v[118:121]
	v_mfma_f32_16x16x32_bf16 v[114:117], v[154:157], v[162:165], v[114:117]
	v_mfma_f32_16x16x32_bf16 v[102:105], v[146:149], v[186:189], v[102:105]
	v_mfma_f32_16x16x32_bf16 v[98:101], v[154:157], v[186:189], v[98:101]
	v_mfma_f32_16x16x32_bf16 v[86:89], v[146:149], v[194:197], v[86:89]
	v_mfma_f32_16x16x32_bf16 v[82:85], v[154:157], v[194:197], v[82:85]
	v_mfma_f32_16x16x32_bf16 v[70:73], v[146:149], v[202:205], v[70:73]
	v_mfma_f32_16x16x32_bf16 v[66:69], v[154:157], v[202:205], v[66:69]
	v_mfma_f32_16x16x32_bf16 v[118:121], v[150:153], v[166:169], v[118:121]
	v_mfma_f32_16x16x32_bf16 v[114:117], v[158:161], v[166:169], v[114:117]
	v_mfma_f32_16x16x32_bf16 v[102:105], v[150:153], v[190:193], v[102:105]
	v_mfma_f32_16x16x32_bf16 v[98:101], v[158:161], v[190:193], v[98:101]
	v_mfma_f32_16x16x32_bf16 v[86:89], v[150:153], v[198:201], v[86:89]
	v_mfma_f32_16x16x32_bf16 v[82:85], v[158:161], v[198:201], v[82:85]
	v_mfma_f32_16x16x32_bf16 v[70:73], v[150:153], v[206:209], v[70:73]
	v_mfma_f32_16x16x32_bf16 v[66:69], v[158:161], v[206:209], v[66:69]
	s_barrier
	s_add_i32 s18, s72, s43
	v_lshl_add_u64 v[216:217], v[216:217], 0, s[8:9]
	s_mov_b32 m0, s18
	ds_read_b128 v[162:165], v214 offset:49152
	ds_read_b128 v[166:169], v214 offset:50176
	ds_read_b128 v[186:189], v214 offset:51200
	ds_read_b128 v[190:193], v214 offset:52224
	ds_read_b128 v[194:197], v214 offset:53248
	ds_read_b128 v[198:201], v214 offset:54272
	ds_read_b128 v[202:205], v214 offset:55296
	ds_read_b128 v[206:209], v214 offset:56320
	global_load_lds_dwordx4 v[216:217], off
	s_add_i32 m0, s18, 0x2000
	s_add_u32 s18, s38, 0x380080
	v_lshl_add_u64 v[216:217], v[218:219], 0, s[8:9]
	s_addc_u32 s19, s39, 0
	s_add_i32 s38, s73, s43
	global_load_lds_dwordx4 v[216:217], off
	v_lshl_add_u64 v[216:217], s[18:19], 0, v[172:173]
	s_mov_b32 m0, s38
	s_nop 0
	global_load_lds_dwordx4 v[216:217], off
	v_lshl_add_u64 v[216:217], s[18:19], 0, v[176:177]
	s_add_i32 m0, s38, 0x2000
	s_nop 0
	global_load_lds_dwordx4 v[216:217], off
	v_lshl_add_u64 v[216:217], v[220:221], 0, s[8:9]
	s_mov_b32 m0, s51
	s_nop 0
	global_load_lds_dwordx4 v[216:217], off
	v_lshl_add_u64 v[216:217], v[222:223], 0, s[8:9]
	s_mov_b32 m0, s54
	s_nop 0
	global_load_lds_dwordx4 v[216:217], off
	s_waitcnt vmcnt(8)
	s_waitcnt lgkmcnt(0)
	s_barrier
	v_mfma_f32_16x16x32_bf16 v[62:65], v[130:133], v[162:165], v[62:65]
	v_mfma_f32_16x16x32_bf16 v[58:61], v[138:141], v[162:165], v[58:61]
	v_mfma_f32_16x16x32_bf16 v[46:49], v[130:133], v[186:189], v[46:49]
	v_mfma_f32_16x16x32_bf16 v[42:45], v[138:141], v[186:189], v[42:45]
	v_mfma_f32_16x16x32_bf16 v[30:33], v[130:133], v[194:197], v[30:33]
	v_mfma_f32_16x16x32_bf16 v[26:29], v[138:141], v[194:197], v[26:29]
	v_mfma_f32_16x16x32_bf16 v[14:17], v[130:133], v[202:205], v[14:17]
	v_mfma_f32_16x16x32_bf16 v[10:13], v[138:141], v[202:205], v[10:13]
	v_mfma_f32_16x16x32_bf16 v[62:65], v[134:137], v[166:169], v[62:65]
	v_mfma_f32_16x16x32_bf16 v[58:61], v[142:145], v[166:169], v[58:61]
	v_mfma_f32_16x16x32_bf16 v[46:49], v[134:137], v[190:193], v[46:49]
	v_mfma_f32_16x16x32_bf16 v[42:45], v[142:145], v[190:193], v[42:45]
	v_mfma_f32_16x16x32_bf16 v[30:33], v[134:137], v[198:201], v[30:33]
	v_mfma_f32_16x16x32_bf16 v[26:29], v[142:145], v[198:201], v[26:29]
	v_mfma_f32_16x16x32_bf16 v[14:17], v[134:137], v[206:209], v[14:17]
	v_mfma_f32_16x16x32_bf16 v[10:13], v[142:145], v[206:209], v[10:13]
	v_mfma_f32_16x16x32_bf16 v[54:57], v[146:149], v[162:165], v[54:57]
	v_mfma_f32_16x16x32_bf16 v[50:53], v[154:157], v[162:165], v[50:53]
	v_mfma_f32_16x16x32_bf16 v[38:41], v[146:149], v[186:189], v[38:41]
	v_mfma_f32_16x16x32_bf16 v[34:37], v[154:157], v[186:189], v[34:37]
	v_mfma_f32_16x16x32_bf16 v[22:25], v[146:149], v[194:197], v[22:25]
	v_mfma_f32_16x16x32_bf16 v[18:21], v[154:157], v[194:197], v[18:21]
	v_mfma_f32_16x16x32_bf16 v[6:9], v[146:149], v[202:205], v[6:9]
	v_mfma_f32_16x16x32_bf16 v[2:5], v[154:157], v[202:205], v[2:5]
	v_mfma_f32_16x16x32_bf16 v[54:57], v[150:153], v[166:169], v[54:57]
	v_mfma_f32_16x16x32_bf16 v[50:53], v[158:161], v[166:169], v[50:53]
	v_mfma_f32_16x16x32_bf16 v[38:41], v[150:153], v[190:193], v[38:41]
	v_mfma_f32_16x16x32_bf16 v[34:37], v[158:161], v[190:193], v[34:37]
	v_mfma_f32_16x16x32_bf16 v[22:25], v[150:153], v[198:201], v[22:25]
	v_mfma_f32_16x16x32_bf16 v[18:21], v[158:161], v[198:201], v[18:21]
	v_mfma_f32_16x16x32_bf16 v[6:9], v[150:153], v[206:209], v[6:9]
	v_mfma_f32_16x16x32_bf16 v[2:5], v[158:161], v[206:209], v[2:5]
	s_barrier
	s_add_i32 s71, s71, 2
	s_add_u32 s69, s69, 0x100
	s_addc_u32 s70, s70, 0
	s_cmpk_gt_u32 s71, 0xdd
	s_mov_b64 s[18:19], s[36:37]
	s_cbranch_scc0 .LBB0_2241
	s_and_b64 vcc, exec, s[10:11]
	s_cbranch_vccz .LBB0_2244
	s_barrier
